# one static s_setprio 1 for the loader waves (0-3) of every role-split k-loop, reset at the join
# speedup vs baseline: 1.0002x; 1.0002x over previous
; DI int opaque_tid() { int t = threadIdx.x; asm volatile("" : "+v"(t)); return t; }
;     constexpr int WM = BM / WR, WN = BN / WC, MT = WM / 16, NT = WN / 16, ROWS = BM + BN, NCH = ROWS * 4, NIT = (NCH + 511) / 512, BUF = ROWS * 64, KT = 32;
;     constexpr int NTS = NT / NSEG, D = NST - 1;
;     static_assert(D == 1 || (NCH % 512 == 0), "deep ring needs a uniform per-thread load count");
;     const int tid = opaque_tid(), lane = tid & 63, wid = tid >> 6, wr = wid / WC, wc = wid % WC, l15 = lane & 15, quad = lane >> 4;
;     const int lrow = tid >> 2, lc = tid & 3;
;     const int lcg = lc ^ ((0 - (tid >> 4)) & 3);
;     const int rsw = (quad ^ ((0 - (l15 >> 2)) & 3)) << 4;
; #pragma unroll
;     for (int mt = 0; mt < MT; ++mt)
; #pragma unroll
;         for (int nt = 0; nt < NT; ++nt) acc[mt][nt] = (f32x4){0.f, 0.f, 0.f, 0.f};
;     const unsigned loff = (unsigned)(lrow * 64 + lcg * 16);
;     const int koff = (int)((blockIdx.x >> 3) + (blockIdx.x & 7) * 4) & (KT - 1);
;     auto issue_one = [&](int kt, int b, int i) {
;         const int row = lrow + 128 * i;
;         if ((NCH % 512 == 0) || (i < NCH / 512) || row < ROWS) {
;             const int kq = (kt + koff) & (KT - 1);
;             const char* ua = (const char*)A + (size_t)((DBG & 1) ? 0 : kq) * (BM * 64);
;             const char* ub = (const char*)Bt + (size_t)((DBG & 2) ? 0 : kq) * ((size_t)ldbk * 2);
;             const char* src;
;             if (BM % 128 == 0) src = (i < BM / 128) ? (ua + i * 8192 + loff) : (ub + (i * 128 - BM) * 64 + loff);
;             else if (i == 0) src = (lrow < BM) ? (ua + loff) : (ub + loff - BM * 64);
;             else src = ub + (i * 128 - BM) * 64 + loff;
;             __builtin_amdgcn_global_load_lds((const unsigned*)src, (unsigned*)(lds + b * BUF + i * 8192 + tid * 16), 16, 0, 0);
;         }
;     };
;     auto issue = [&](int kt, int b) {
; #pragma unroll
;         for (int i = 0; i < NIT; ++i) issue_one(kt, b, i);
.LBB0_96:
	s_or_b64 exec, exec, s[8:9]
	v_ashrrev_i32_e32 v3, 6, v2
	v_lshrrev_b32_e32 v4, 29, v3
	v_add_u32_e32 v4, v3, v4
	v_lshlrev_b32_e32 v6, 2, v2
	v_ashrrev_i32_e32 v4, 3, v4
	v_and_b32_e32 v6, 48, v6
	v_mul_i32_i24_e32 v5, 8, v4
	v_sub_u32_e32 v6, 0, v6
	v_sub_u32_e32 v3, v3, v5
	v_bitop3_b32 v5, v2, 48, v6 bitop3:0x48
	v_lshlrev_b32_e32 v2, 6, v2
	v_and_b32_e32 v2, 0x3c0, v2
	v_lshl_or_b32 v141, v3, 13, v2
	v_lshl_or_b32 v139, v4, 12, v2
	v_mov_b32_e32 v2, 0
	s_mov_b32 s8, 0
	v_add_u32_e32 v140, 0, v5
	v_lshl_add_u64 v[130:131], s[6:7], 0, v[0:1]
	v_lshl_add_u64 v[132:133], s[70:71], 0, v[0:1]
	s_mov_b32 s9, 1
	v_readlane_b32 s46, v243, 23
	s_mov_b32 s47, 1
	v_mov_b32_e32 v3, v2
	v_mov_b32_e32 v4, v2
	v_mov_b32_e32 v5, v2
	v_mov_b32_e32 v38, v2
	v_mov_b32_e32 v39, v2
	v_mov_b32_e32 v40, v2
	v_mov_b32_e32 v41, v2
	v_mov_b32_e32 v42, v2
	v_mov_b32_e32 v43, v2
	v_mov_b32_e32 v44, v2
	v_mov_b32_e32 v45, v2
	v_mov_b32_e32 v46, v2
	v_mov_b32_e32 v47, v2
	v_mov_b32_e32 v48, v2
	v_mov_b32_e32 v49, v2
	v_mov_b32_e32 v50, v2
	v_mov_b32_e32 v51, v2
	v_mov_b32_e32 v52, v2
	v_mov_b32_e32 v53, v2
	v_mov_b32_e32 v54, v2
	v_mov_b32_e32 v55, v2
	v_mov_b32_e32 v56, v2
	v_mov_b32_e32 v57, v2
	v_mov_b32_e32 v58, v2
	v_mov_b32_e32 v59, v2
	v_mov_b32_e32 v60, v2
	v_mov_b32_e32 v61, v2
	v_mov_b32_e32 v62, v2
	v_mov_b32_e32 v63, v2
	v_mov_b32_e32 v64, v2
	v_mov_b32_e32 v65, v2
	v_mov_b32_e32 v6, v2
	v_mov_b32_e32 v7, v2
	v_mov_b32_e32 v8, v2
	v_mov_b32_e32 v9, v2
	v_mov_b32_e32 v10, v2
	v_mov_b32_e32 v11, v2
	v_mov_b32_e32 v12, v2
	v_mov_b32_e32 v13, v2
	v_mov_b32_e32 v14, v2
	v_mov_b32_e32 v15, v2
	v_mov_b32_e32 v16, v2
	v_mov_b32_e32 v17, v2
	v_mov_b32_e32 v18, v2
	v_mov_b32_e32 v19, v2
	v_mov_b32_e32 v20, v2
	v_mov_b32_e32 v21, v2
	v_mov_b32_e32 v22, v2
	v_mov_b32_e32 v23, v2
	v_mov_b32_e32 v24, v2
	v_mov_b32_e32 v25, v2
	v_mov_b32_e32 v26, v2
	v_mov_b32_e32 v27, v2
	v_mov_b32_e32 v28, v2
	v_mov_b32_e32 v29, v2
	v_mov_b32_e32 v30, v2
	v_mov_b32_e32 v31, v2
	v_mov_b32_e32 v32, v2
	v_mov_b32_e32 v33, v2
	v_mov_b32_e32 v34, v2
	v_mov_b32_e32 v35, v2
	v_mov_b32_e32 v36, v2
	v_mov_b32_e32 v37, v2
	v_mov_b32_e32 v66, v2
	v_mov_b32_e32 v67, v2
	v_mov_b32_e32 v68, v2
	v_mov_b32_e32 v69, v2
	v_mov_b32_e32 v102, v2
	v_mov_b32_e32 v103, v2
	v_mov_b32_e32 v104, v2
	v_mov_b32_e32 v105, v2
	v_mov_b32_e32 v106, v2
	v_mov_b32_e32 v107, v2
	v_mov_b32_e32 v108, v2
	v_mov_b32_e32 v109, v2
	v_mov_b32_e32 v110, v2
	v_mov_b32_e32 v111, v2
	v_mov_b32_e32 v112, v2
	v_mov_b32_e32 v113, v2
	v_mov_b32_e32 v114, v2
	v_mov_b32_e32 v115, v2
	s_waitcnt lgkmcnt(0)
	v_mov_b32_e32 v116, v2
	v_mov_b32_e32 v117, v2
	v_mov_b32_e32 v118, v2
	v_mov_b32_e32 v119, v2
	v_mov_b32_e32 v120, v2
	v_mov_b32_e32 v121, v2
	v_mov_b32_e32 v122, v2
	v_mov_b32_e32 v123, v2
	v_mov_b32_e32 v124, v2
	v_mov_b32_e32 v125, v2
	v_mov_b32_e32 v126, v2
	v_mov_b32_e32 v127, v2
	v_mov_b32_e32 v128, v2
	v_mov_b32_e32 v129, v2
	v_mov_b32_e32 v70, v2
	v_mov_b32_e32 v71, v2
	v_mov_b32_e32 v72, v2
	v_mov_b32_e32 v73, v2
	v_mov_b32_e32 v74, v2
	v_mov_b32_e32 v75, v2
	v_mov_b32_e32 v76, v2
	v_mov_b32_e32 v77, v2
	v_mov_b32_e32 v78, v2
	v_mov_b32_e32 v79, v2
	v_mov_b32_e32 v80, v2
	v_mov_b32_e32 v81, v2
	v_mov_b32_e32 v82, v2
	v_mov_b32_e32 v83, v2
	v_mov_b32_e32 v84, v2
	v_mov_b32_e32 v85, v2
	v_mov_b32_e32 v86, v2
	v_mov_b32_e32 v87, v2
	v_mov_b32_e32 v88, v2
	v_mov_b32_e32 v89, v2
	v_mov_b32_e32 v90, v2
	v_mov_b32_e32 v91, v2
	v_mov_b32_e32 v92, v2
	v_mov_b32_e32 v93, v2
	v_mov_b32_e32 v94, v2
	v_mov_b32_e32 v95, v2
	v_mov_b32_e32 v96, v2
	v_mov_b32_e32 v97, v2
	v_mov_b32_e32 v98, v2
	v_mov_b32_e32 v99, v2
	v_mov_b32_e32 v100, v2
	v_mov_b32_e32 v101, v2
	v_readfirstlane_b32 s40, v212
	s_nop 3
	s_cmp_lt_u32 s40, 0x100
	s_cbranch_scc0 .Lpo1_c_entry
	s_setprio 1
	s_cmp_lt_u32 s40, 0x80
	s_cselect_b32 s49, 1, 0
	s_lshl_b32 s46, s40, 4
	v_add_u32_e32 v199, s46, v0
	s_lshl_b32 s40, s40, 5
	v_readfirstlane_b32 s46, v130
	v_readfirstlane_b32 s47, v131
	v_readfirstlane_b32 s6, v0
	s_nop 3
	s_sub_u32 vcc_lo, s46, s6
	s_subb_u32 vcc_hi, s47, 0
	s_mov_b32 s9, 1
	s_add_i32 s46, s33, s9
	s_and_b32 s46, s46, 31
	s_lshl_b32 s6, s46, 16
	s_lshl_b32 s46, s46, 12
	s_add_u32 s46, vcc_lo, s46
	s_addc_u32 s47, vcc_hi, 0
	s_add_u32 s6, s70, s6
	s_addc_u32 s7, s71, 0
	s_sub_u32 s6, s6, 0x1000
	s_subb_u32 s7, s7, 0
	s_bitcmp1_b32 s9, 0
	s_cselect_b32 m0, 0x11000, 0
	s_add_u32 m0, m0, s40
	s_cmp_lg_u32 s49, 0
	s_cbranch_scc0 .Lpo1_s0b_1
	global_load_lds_dwordx4 v199, s[46:47]
	global_load_lds_dwordx4 v199, s[46:47] offset:1024
	s_branch .Lpo1_s0d_1

; template <int N> DI void wait_vm() { asm volatile("s_waitcnt vmcnt(%0)" ::"n"(N) : "memory"); }
; DI void raw_barrier() { asm volatile("" ::: "memory"); __builtin_amdgcn_s_barrier(); asm volatile("" ::: "memory"); }
;     ...
;     for (int kt = 0; kt < KT; ++kt) {
;         if (D > 1 && kt + D - 1 < KT) wait_vm<(D - 1) * NIT>(); else wait_vm<0>();
;         raw_barrier();
;         compute(cb, kt + D < KT, kt + D, ib);
;         cb = (cb + 1 == NST) ? 0 : cb + 1;
;         ib = (ib + 1 == NST) ? 0 : ib + 1;
;     }
;     __syncthreads();
.Lpo1_join:
	s_setprio 0

; DI int opaque_tid() { int t = threadIdx.x; asm volatile("" : "+v"(t)); return t; }
;     constexpr int WM = BM / WR, WN = BN / WC, MT = WM / 16, NT = WN / 16, ROWS = BM + BN, NCH = ROWS * 4, NIT = (NCH + 511) / 512, BUF = ROWS * 64, KT = 32;
;     constexpr int NTS = NT / NSEG, D = NST - 1;
;     static_assert(D == 1 || (NCH % 512 == 0), "deep ring needs a uniform per-thread load count");
;     const int tid = opaque_tid(), lane = tid & 63, wid = tid >> 6, wr = wid / WC, wc = wid % WC, l15 = lane & 15, quad = lane >> 4;
;     const int lrow = tid >> 2, lc = tid & 3;
;     const int lcg = lc ^ ((0 - (tid >> 4)) & 3);
;     const int rsw = (quad ^ ((0 - (l15 >> 2)) & 3)) << 4;
; #pragma unroll
;     for (int mt = 0; mt < MT; ++mt)
; #pragma unroll
;         for (int nt = 0; nt < NT; ++nt) acc[mt][nt] = (f32x4){0.f, 0.f, 0.f, 0.f};
;     const unsigned loff = (unsigned)(lrow * 64 + lcg * 16);
;     const int koff = (int)((blockIdx.x >> 3) + (blockIdx.x & 7) * 4) & (KT - 1);
;     auto issue_one = [&](int kt, int b, int i) {
;         const int row = lrow + 128 * i;
;         if ((NCH % 512 == 0) || (i < NCH / 512) || row < ROWS) {
;             const int kq = (kt + koff) & (KT - 1);
;             const char* ua = (const char*)A + (size_t)((DBG & 1) ? 0 : kq) * (BM * 64);
;             const char* ub = (const char*)Bt + (size_t)((DBG & 2) ? 0 : kq) * ((size_t)ldbk * 2);
;             const char* src;
;             if (BM % 128 == 0) src = (i < BM / 128) ? (ua + i * 8192 + loff) : (ub + (i * 128 - BM) * 64 + loff);
;             else if (i == 0) src = (lrow < BM) ? (ua + loff) : (ub + loff - BM * 64);
;             else src = ub + (i * 128 - BM) * 64 + loff;
;             __builtin_amdgcn_global_load_lds((const unsigned*)src, (unsigned*)(lds + b * BUF + i * 8192 + tid * 16), 16, 0, 0);
;         }
;     };
;     auto issue = [&](int kt, int b) {
; #pragma unroll
;         for (int i = 0; i < NIT; ++i) issue_one(kt, b, i);
.LBB0_378:
	s_or_b64 exec, exec, s[28:29]
	v_ashrrev_i32_e32 v3, 6, v2
	v_lshrrev_b32_e32 v4, 29, v3
	v_add_u32_e32 v4, v3, v4
	v_lshlrev_b32_e32 v6, 2, v2
	v_ashrrev_i32_e32 v4, 3, v4
	v_and_b32_e32 v6, 48, v6
	v_mul_i32_i24_e32 v5, 8, v4
	v_sub_u32_e32 v6, 0, v6
	v_sub_u32_e32 v3, v3, v5
	v_bitop3_b32 v5, v2, 48, v6 bitop3:0x48
	v_lshlrev_b32_e32 v2, 6, v2
	v_and_b32_e32 v2, 0x3c0, v2
	v_lshl_or_b32 v141, v3, 13, v2
	v_lshl_or_b32 v139, v4, 12, v2
	v_mov_b32_e32 v2, 0
	s_mov_b32 s28, 0
	v_add_u32_e32 v140, 0, v5
	v_lshl_add_u64 v[130:131], s[8:9], 0, v[0:1]
	v_lshl_add_u64 v[132:133], s[18:19], 0, v[0:1]
	s_mov_b32 s29, 1
	v_readlane_b32 s46, v243, 23
	s_mov_b32 s47, 1
	v_mov_b32_e32 v3, v2
	v_mov_b32_e32 v4, v2
	v_mov_b32_e32 v5, v2
	v_mov_b32_e32 v38, v2
	v_mov_b32_e32 v39, v2
	v_mov_b32_e32 v40, v2
	v_mov_b32_e32 v41, v2
	v_mov_b32_e32 v42, v2
	v_mov_b32_e32 v43, v2
	v_mov_b32_e32 v44, v2
	v_mov_b32_e32 v45, v2
	v_mov_b32_e32 v46, v2
	v_mov_b32_e32 v47, v2
	v_mov_b32_e32 v48, v2
	v_mov_b32_e32 v49, v2
	v_mov_b32_e32 v50, v2
	v_mov_b32_e32 v51, v2
	v_mov_b32_e32 v52, v2
	v_mov_b32_e32 v53, v2
	v_mov_b32_e32 v54, v2
	v_mov_b32_e32 v55, v2
	v_mov_b32_e32 v56, v2
	v_mov_b32_e32 v57, v2
	v_mov_b32_e32 v58, v2
	v_mov_b32_e32 v59, v2
	v_mov_b32_e32 v60, v2
	v_mov_b32_e32 v61, v2
	v_mov_b32_e32 v62, v2
	v_mov_b32_e32 v63, v2
	v_mov_b32_e32 v64, v2
	v_mov_b32_e32 v65, v2
	v_mov_b32_e32 v6, v2
	v_mov_b32_e32 v7, v2
	v_mov_b32_e32 v8, v2
	v_mov_b32_e32 v9, v2
	v_mov_b32_e32 v10, v2
	v_mov_b32_e32 v11, v2
	v_mov_b32_e32 v12, v2
	v_mov_b32_e32 v13, v2
	v_mov_b32_e32 v14, v2
	v_mov_b32_e32 v15, v2
	v_mov_b32_e32 v16, v2
	v_mov_b32_e32 v17, v2
	v_mov_b32_e32 v18, v2
	v_mov_b32_e32 v19, v2
	v_mov_b32_e32 v20, v2
	v_mov_b32_e32 v21, v2
	v_mov_b32_e32 v22, v2
	v_mov_b32_e32 v23, v2
	v_mov_b32_e32 v24, v2
	v_mov_b32_e32 v25, v2
	v_mov_b32_e32 v26, v2
	v_mov_b32_e32 v27, v2
	v_mov_b32_e32 v28, v2
	v_mov_b32_e32 v29, v2
	v_mov_b32_e32 v30, v2
	v_mov_b32_e32 v31, v2
	v_mov_b32_e32 v32, v2
	v_mov_b32_e32 v33, v2
	v_mov_b32_e32 v34, v2
	v_mov_b32_e32 v35, v2
	v_mov_b32_e32 v36, v2
	v_mov_b32_e32 v37, v2
	v_mov_b32_e32 v66, v2
	v_mov_b32_e32 v67, v2
	v_mov_b32_e32 v68, v2
	v_mov_b32_e32 v69, v2
	v_mov_b32_e32 v102, v2
	v_mov_b32_e32 v103, v2
	v_mov_b32_e32 v104, v2
	v_mov_b32_e32 v105, v2
	v_mov_b32_e32 v106, v2
	v_mov_b32_e32 v107, v2
	v_mov_b32_e32 v108, v2
	v_mov_b32_e32 v109, v2
	v_mov_b32_e32 v110, v2
	v_mov_b32_e32 v111, v2
	v_mov_b32_e32 v112, v2
	v_mov_b32_e32 v113, v2
	v_mov_b32_e32 v114, v2
	v_mov_b32_e32 v115, v2
	v_mov_b32_e32 v116, v2
	v_mov_b32_e32 v117, v2
	v_mov_b32_e32 v118, v2
	v_mov_b32_e32 v119, v2
	v_mov_b32_e32 v120, v2
	v_mov_b32_e32 v121, v2
	v_mov_b32_e32 v122, v2
	v_mov_b32_e32 v123, v2
	v_mov_b32_e32 v124, v2
	v_mov_b32_e32 v125, v2
	v_mov_b32_e32 v126, v2
	v_mov_b32_e32 v127, v2
	v_mov_b32_e32 v128, v2
	v_mov_b32_e32 v129, v2
	v_mov_b32_e32 v70, v2
	v_mov_b32_e32 v71, v2
	v_mov_b32_e32 v72, v2
	v_mov_b32_e32 v73, v2
	v_mov_b32_e32 v74, v2
	v_mov_b32_e32 v75, v2
	v_mov_b32_e32 v76, v2
	v_mov_b32_e32 v77, v2
	v_mov_b32_e32 v78, v2
	v_mov_b32_e32 v79, v2
	v_mov_b32_e32 v80, v2
	v_mov_b32_e32 v81, v2
	v_mov_b32_e32 v82, v2
	v_mov_b32_e32 v83, v2
	v_mov_b32_e32 v84, v2
	v_mov_b32_e32 v85, v2
	v_mov_b32_e32 v86, v2
	v_mov_b32_e32 v87, v2
	v_mov_b32_e32 v88, v2
	v_mov_b32_e32 v89, v2
	v_mov_b32_e32 v90, v2
	v_mov_b32_e32 v91, v2
	v_mov_b32_e32 v92, v2
	v_mov_b32_e32 v93, v2
	v_mov_b32_e32 v94, v2
	v_mov_b32_e32 v95, v2
	v_mov_b32_e32 v96, v2
	v_mov_b32_e32 v97, v2
	v_mov_b32_e32 v98, v2
	v_mov_b32_e32 v99, v2
	v_mov_b32_e32 v100, v2
	v_mov_b32_e32 v101, v2
	v_readfirstlane_b32 s40, v212
	s_nop 3
	s_cmp_lt_u32 s40, 0x100
	s_cbranch_scc0 .Lpo2_c_entry
	s_setprio 1
	s_cmp_lt_u32 s40, 0x80
	s_cselect_b32 s72, 1, 0
	s_lshl_b32 s46, s40, 4
	v_add_u32_e32 v199, s46, v0
	s_lshl_b32 s40, s40, 5
	v_readfirstlane_b32 s46, v130
	v_readfirstlane_b32 s47, v131
	v_readfirstlane_b32 s8, v0
	s_nop 3
	s_sub_u32 vcc_lo, s46, s8
	s_subb_u32 vcc_hi, s47, 0
	s_mov_b32 s29, 1
	s_add_i32 s46, s33, s29
	s_and_b32 s46, s46, 31
	s_lshl_b32 s8, s46, 16
	s_lshl_b32 s46, s46, 12
	s_add_u32 s46, vcc_lo, s46
	s_addc_u32 s47, vcc_hi, 0
	s_add_u32 s8, s18, s8
	s_addc_u32 s9, s19, 0
	s_sub_u32 s8, s8, 0x1000
	s_subb_u32 s9, s9, 0
	s_bitcmp1_b32 s29, 0
	s_cselect_b32 m0, 0x11000, 0
	s_add_u32 m0, m0, s40
	s_cmp_lg_u32 s72, 0
	s_cbranch_scc0 .Lpo2_s0b_1
	global_load_lds_dwordx4 v199, s[46:47]
	global_load_lds_dwordx4 v199, s[46:47] offset:1024
	s_branch .Lpo2_s0d_1

; DI int opaque_tid() { int t = threadIdx.x; asm volatile("" : "+v"(t)); return t; }
;     constexpr int WM = BM / WR, WN = BN / WC, MT = WM / 16, NT = WN / 16, ROWS = BM + BN, NCH = ROWS * 4, NIT = (NCH + 511) / 512, BUF = ROWS * 64, KT = 32;
;     constexpr int NTS = NT / NSEG, D = NST - 1;
;     static_assert(D == 1 || (NCH % 512 == 0), "deep ring needs a uniform per-thread load count");
;     const int tid = opaque_tid(), lane = tid & 63, wid = tid >> 6, wr = wid / WC, wc = wid % WC, l15 = lane & 15, quad = lane >> 4;
;     const int lrow = tid >> 2, lc = tid & 3;
;     const int lcg = lc ^ ((0 - (tid >> 4)) & 3);
;     const int rsw = (quad ^ ((0 - (l15 >> 2)) & 3)) << 4;
; #pragma unroll
;     for (int mt = 0; mt < MT; ++mt)
; #pragma unroll
;         for (int nt = 0; nt < NT; ++nt) acc[mt][nt] = (f32x4){0.f, 0.f, 0.f, 0.f};
;     const unsigned loff = (unsigned)(lrow * 64 + lcg * 16);
;     const int koff = (int)((blockIdx.x >> 3) + (blockIdx.x & 7) * 4) & (KT - 1);
;     auto issue_one = [&](int kt, int b, int i) {
;         const int row = lrow + 128 * i;
;         if ((NCH % 512 == 0) || (i < NCH / 512) || row < ROWS) {
;             const int kq = (kt + koff) & (KT - 1);
;             const char* ua = (const char*)A + (size_t)((DBG & 1) ? 0 : kq) * (BM * 64);
;             const char* ub = (const char*)Bt + (size_t)((DBG & 2) ? 0 : kq) * ((size_t)ldbk * 2);
;             const char* src;
;             if (BM % 128 == 0) src = (i < BM / 128) ? (ua + i * 8192 + loff) : (ub + (i * 128 - BM) * 64 + loff);
;             else if (i == 0) src = (lrow < BM) ? (ua + loff) : (ub + loff - BM * 64);
;             else src = ub + (i * 128 - BM) * 64 + loff;
;             __builtin_amdgcn_global_load_lds((const unsigned*)src, (unsigned*)(lds + b * BUF + i * 8192 + tid * 16), 16, 0, 0);
;         }
;     };
;     auto issue = [&](int kt, int b) {
; #pragma unroll
;         for (int i = 0; i < NIT; ++i) issue_one(kt, b, i);
;     ...
;     __syncthreads();
; #pragma unroll
;     for (int d = 0; d < D; ++d) issue(d, d);
; DI void unit_X(const Params& p, char* lds, int l, int chunk) {
;     ...
;     bf16_t* gx = WS_PTR(bf16_t, OFF_GX) + (size_t)chunk * 128 * 256;
;     {
;         f32x4 acc[4][8];
;         gemm_main<128, 512, 2, 4, 1, true, 3>(xb + (size_t)chunk * 128 * 1024, WS_PTR(const bf16_t, OFF_WIN) + (size_t)l * 2560 * 1024 + (size_t)2048 * 32, 2560 * 32, lds, acc);
.LBB0_740:
	s_and_b64 vcc, exec, s[6:7]
	s_cbranch_vccz .LBB0_824
	v_mov_b32_e32 v137, v212
	v_mov_b32_e32 v4, v212
	s_lshl_b32 s0, s40, 5
	v_ashrrev_i32_e32 v5, 6, v4
	v_lshrrev_b32_e32 v0, 30, v5
	v_add_u32_e32 v0, v5, v0
	v_ashrrev_i32_e32 v6, 2, v0
	v_lshrrev_b32_e32 v0, 4, v4
	s_or_b32 s8, s0, s73
	v_sub_u32_e32 v0, 0, v0
	v_lshlrev_b32_e32 v2, 2, v4
	s_lshl_b32 s13, s8, 7
	s_lshl_b32 s0, s8, 18
	v_readlane_b32 s1, v243, 56
	v_and_b32_e32 v2, 48, v2
	v_xor_b32_e32 v0, v4, v0
	v_lshlrev_b32_e32 v8, 4, v4
	s_add_u32 s10, s1, s0
	v_readlane_b32 s0, v243, 40
	v_sub_u32_e32 v7, 0, v2
	v_and_b32_e32 v2, 0xffffffc0, v8
	v_lshlrev_b32_e32 v0, 4, v0
	s_addc_u32 s11, s0, 0
	v_and_or_b32 v0, v0, 48, v2
	v_lshl_add_u64 v[130:131], s[10:11], 0, v[0:1]
	v_readlane_b32 s10, v243, 25
	v_add_u32_e32 v134, 0, v8
	v_readlane_b32 s11, v243, 26
	v_readfirstlane_b32 s7, v134
	s_mov_b32 m0, s7
	v_lshl_add_u64 v[2:3], v[130:131], 0, s[10:11]
	s_barrier
	global_load_lds_dwordx4 v[2:3], off
	v_add_u32_e32 v2, 0x2000, v134
	v_readlane_b32 s10, v242, 7
	v_readfirstlane_b32 s7, v2
	s_mov_b32 m0, s7
	v_readlane_b32 s11, v242, 8
	v_add_u32_e32 v2, 0x4000, v134
	v_add_u32_e32 v9, 0xa000, v134
	v_readfirstlane_b32 s7, v2
	v_add_u32_e32 v2, 0x6000, v134
	s_add_i32 s12, 0, 0x10000
	global_load_lds_dwordx4 v0, s[10:11]
	v_readlane_b32 s10, v242, 3
	s_mov_b32 m0, s7
	v_readlane_b32 s11, v242, 4
	v_readfirstlane_b32 s7, v2
	v_add_u32_e32 v2, 0x8000, v134
	s_mov_b32 s1, 2
	s_mov_b32 s0, 4
	s_mov_b32 s6, 0
	global_load_lds_dwordx4 v0, s[10:11]
	v_readlane_b32 s10, v242, 5
	s_mov_b32 m0, s7
	v_readlane_b32 s11, v242, 6
	v_readfirstlane_b32 s7, v2
	v_lshl_add_u64 v[132:133], s[50:51], 0, v[0:1]
	s_nop 2
	global_load_lds_dwordx4 v0, s[10:11]
	v_readlane_b32 s10, v242, 9
	s_mov_b32 m0, s7
	v_readlane_b32 s11, v242, 10
	v_readfirstlane_b32 s7, v9
	s_nop 3
	global_load_lds_dwordx4 v0, s[10:11]
	v_readlane_b32 s10, v243, 5
	v_readlane_b32 s11, v243, 6
	s_mov_b32 m0, s7
	s_nop 0
	v_lshl_add_u64 v[2:3], v[130:131], 0, s[10:11]
	global_load_lds_dwordx4 v[2:3], off
	v_add_u32_e32 v2, 0xc000, v134
	v_readlane_b32 s10, v242, 15
	v_readfirstlane_b32 s7, v2
	s_mov_b32 m0, s7
	v_readlane_b32 s11, v242, 16
	v_add_u32_e32 v2, 0xe000, v134
	v_bitop3_b32 v3, v4, 48, v7 bitop3:0x48
	v_readfirstlane_b32 s7, v2
	v_add_u32_e32 v2, s12, v8
	v_add_u32_e32 v135, 0, v3
	global_load_lds_dwordx4 v0, s[10:11]
	v_readlane_b32 s10, v242, 11
	s_mov_b32 m0, s7
	v_readlane_b32 s11, v242, 12
	v_readfirstlane_b32 s7, v2
	v_lshlrev_b32_e32 v3, 6, v4
	v_and_b32_e32 v3, 0x3c0, v3
	v_lshl_or_b32 v136, v6, 12, v3
	s_nop 0
	global_load_lds_dwordx4 v0, s[10:11]
	s_mov_b32 m0, s7
	v_readlane_b32 s10, v242, 13
	v_readlane_b32 s7, v243, 31
	v_readlane_b32 s11, v242, 14
	s_nop 0
	v_add_u32_e32 v2, s7, v8
	s_nop 0
	v_readfirstlane_b32 s7, v2
	v_mul_i32_i24_e32 v2, 4, v6
	global_load_lds_dwordx4 v0, s[10:11]
	v_readlane_b32 s10, v242, 17
	s_mov_b32 m0, s7
	v_readlane_b32 s11, v242, 18
	v_sub_u32_e32 v2, v5, v2
	v_lshl_or_b32 v138, v2, 13, v3
	v_mov_b32_e32 v2, 0
	v_readlane_b32 s7, v243, 24
	v_mov_b32_e32 v3, v2
	global_load_lds_dwordx4 v0, s[10:11]
	v_mov_b32_e32 v4, v2
	v_mov_b32_e32 v5, v2
	v_mov_b32_e32 v6, v2
	v_mov_b32_e32 v7, v2
	v_mov_b32_e32 v8, v2
	v_mov_b32_e32 v9, v2
	v_mov_b32_e32 v10, v2
	v_mov_b32_e32 v11, v2
	v_mov_b32_e32 v12, v2
	v_mov_b32_e32 v13, v2
	v_mov_b32_e32 v14, v2
	v_mov_b32_e32 v15, v2
	v_mov_b32_e32 v16, v2
	v_mov_b32_e32 v17, v2
	v_mov_b32_e32 v18, v2
	v_mov_b32_e32 v19, v2
	v_mov_b32_e32 v20, v2
	v_mov_b32_e32 v21, v2
	v_mov_b32_e32 v22, v2
	v_mov_b32_e32 v23, v2
	v_mov_b32_e32 v24, v2
	v_mov_b32_e32 v25, v2
	v_mov_b32_e32 v26, v2
	v_mov_b32_e32 v27, v2
	v_mov_b32_e32 v28, v2
	v_mov_b32_e32 v29, v2
	v_mov_b32_e32 v30, v2
	v_mov_b32_e32 v31, v2
	v_mov_b32_e32 v32, v2
	v_mov_b32_e32 v33, v2
	v_mov_b32_e32 v34, v2
	v_mov_b32_e32 v35, v2
	v_mov_b32_e32 v36, v2
	v_mov_b32_e32 v37, v2
	v_mov_b32_e32 v38, v2
	v_mov_b32_e32 v39, v2
	v_mov_b32_e32 v40, v2
	v_mov_b32_e32 v41, v2
	v_mov_b32_e32 v42, v2
	v_mov_b32_e32 v43, v2
	v_mov_b32_e32 v44, v2
	v_mov_b32_e32 v45, v2
	v_mov_b32_e32 v46, v2
	v_mov_b32_e32 v47, v2
	v_mov_b32_e32 v48, v2
	v_mov_b32_e32 v49, v2
	v_mov_b32_e32 v50, v2
	v_mov_b32_e32 v51, v2
	v_mov_b32_e32 v52, v2
	v_mov_b32_e32 v53, v2
	v_mov_b32_e32 v54, v2
	v_mov_b32_e32 v55, v2
	v_mov_b32_e32 v56, v2
	v_mov_b32_e32 v57, v2
	v_mov_b32_e32 v58, v2
	v_mov_b32_e32 v59, v2
	v_mov_b32_e32 v60, v2
	v_mov_b32_e32 v61, v2
	v_mov_b32_e32 v62, v2
	v_mov_b32_e32 v63, v2
	v_mov_b32_e32 v64, v2
	v_mov_b32_e32 v65, v2
	v_mov_b32_e32 v66, v2
	v_mov_b32_e32 v67, v2
	v_mov_b32_e32 v68, v2
	v_mov_b32_e32 v69, v2
	v_mov_b32_e32 v70, v2
	v_mov_b32_e32 v71, v2
	v_mov_b32_e32 v72, v2
	v_mov_b32_e32 v73, v2
	v_mov_b32_e32 v74, v2
	v_mov_b32_e32 v75, v2
	v_mov_b32_e32 v76, v2
	v_mov_b32_e32 v77, v2
	v_mov_b32_e32 v78, v2
	v_mov_b32_e32 v79, v2
	v_mov_b32_e32 v80, v2
	v_mov_b32_e32 v81, v2
	v_mov_b32_e32 v82, v2
	v_mov_b32_e32 v83, v2
	v_mov_b32_e32 v84, v2
	v_mov_b32_e32 v85, v2
	v_mov_b32_e32 v86, v2
	v_mov_b32_e32 v87, v2
	v_mov_b32_e32 v88, v2
	v_mov_b32_e32 v89, v2
	v_mov_b32_e32 v90, v2
	v_mov_b32_e32 v91, v2
	v_mov_b32_e32 v92, v2
	v_mov_b32_e32 v93, v2
	v_mov_b32_e32 v94, v2
	v_mov_b32_e32 v95, v2
	v_mov_b32_e32 v96, v2
	v_mov_b32_e32 v97, v2
	v_mov_b32_e32 v98, v2
	v_mov_b32_e32 v99, v2
	v_mov_b32_e32 v100, v2
	v_mov_b32_e32 v101, v2
	v_mov_b32_e32 v102, v2
	v_mov_b32_e32 v103, v2
	v_mov_b32_e32 v104, v2
	v_mov_b32_e32 v105, v2
	v_mov_b32_e32 v106, v2
	v_mov_b32_e32 v107, v2
	v_mov_b32_e32 v108, v2
	v_mov_b32_e32 v109, v2
	v_mov_b32_e32 v110, v2
	v_mov_b32_e32 v111, v2
	v_mov_b32_e32 v112, v2
	v_mov_b32_e32 v113, v2
	v_mov_b32_e32 v114, v2
	v_mov_b32_e32 v115, v2
	s_waitcnt lgkmcnt(0)
	v_mov_b32_e32 v116, v2
	v_mov_b32_e32 v117, v2
	v_mov_b32_e32 v118, v2
	v_mov_b32_e32 v119, v2
	v_mov_b32_e32 v120, v2
	v_mov_b32_e32 v121, v2
	v_mov_b32_e32 v122, v2
	v_mov_b32_e32 v123, v2
	v_mov_b32_e32 v124, v2
	v_mov_b32_e32 v125, v2
	v_mov_b32_e32 v126, v2
	v_mov_b32_e32 v127, v2
	v_mov_b32_e32 v128, v2
	v_mov_b32_e32 v129, v2
	v_readfirstlane_b32 s9, v212
	s_nop 3
	s_cmp_lt_u32 s9, 0x100
	s_cbranch_scc0 .Lpx_c_entry
; template <int N> DI void wait_vm() { asm volatile("s_waitcnt vmcnt(%0)" ::"n"(N) : "memory"); }
; DI void raw_barrier() { asm volatile("" ::: "memory"); __builtin_amdgcn_s_barrier(); asm volatile("" ::: "memory"); }
;     ...
;     auto issue_one = [&](int kt, int b, int i) {
;         const int row = lrow + 128 * i;
;         if ((NCH % 512 == 0) || (i < NCH / 512) || row < ROWS) {
;             const int kq = (kt + koff) & (KT - 1);
;             const char* ua = (const char*)A + (size_t)((DBG & 1) ? 0 : kq) * (BM * 64);
;             const char* ub = (const char*)Bt + (size_t)((DBG & 2) ? 0 : kq) * ((size_t)ldbk * 2);
;             const char* src;
;             if (BM % 128 == 0) src = (i < BM / 128) ? (ua + i * 8192 + loff) : (ub + (i * 128 - BM) * 64 + loff);
;             else if (i == 0) src = (lrow < BM) ? (ua + loff) : (ub + loff - BM * 64);
;             else src = ub + (i * 128 - BM) * 64 + loff;
;             __builtin_amdgcn_global_load_lds((const unsigned*)src, (unsigned*)(lds + b * BUF + i * 8192 + tid * 16), 16, 0, 0);
;         }
;     };
;     auto issue = [&](int kt, int b) {
; #pragma unroll
;         for (int i = 0; i < NIT; ++i) issue_one(kt, b, i);
;     };
;     auto compute = [&](int cb, bool do_issue, int ikt, int ib) {
;         const char* base = lds + cb * BUF;
;         bf16x8 af[MT], bfr[NT];
; #pragma unroll
;         for (int nt = 0; nt < NT; ++nt) {
;             const int br = BM + (nt / NTS) * (BN / NSEG) + wc * (NTS * 16) + (nt % NTS) * 16;
;             bfr[nt] = *(const bf16x8*)(base + (br + l15) * 64 + rsw);
;         }
; #pragma unroll
;         for (int mt = 0; mt < MT; ++mt) af[mt] = *(const bf16x8*)(base + (wr * WM + mt * 16 + l15) * 64 + rsw);
;     ...
;     for (int d = 0; d < D; ++d) issue(d, d);
;     int cb = 0, ib = D;
;     for (int kt = 0; kt < KT; ++kt) {
;         if (D > 1 && kt + D - 1 < KT) wait_vm<(D - 1) * NIT>(); else wait_vm<0>();
;         raw_barrier();
	s_setprio 1
	s_lshl_b32 s7, s9, 5
	s_lshl_b32 s40, s9, 4
	v_add_u32_e32 v227, s40, v0
	v_readfirstlane_b32 s10, v130
	v_readfirstlane_b32 s11, v131
	v_readfirstlane_b32 s40, v0
	s_nop 3
	s_sub_u32 vcc_lo, s10, s40
	s_subb_u32 vcc_hi, s11, 0
	s_mul_i32 s10, s1, 0xa000
	s_add_u32 s10, s10, s7
	s_mov_b32 m0, s10
	s_add_i32 s40, s59, s0
	s_and_b32 s40, s40, 62
	s_lshl_b32 s10, s40, 12
	s_add_u32 s10, vcc_lo, s10
	s_addc_u32 s11, vcc_hi, 0
	s_mul_i32 s40, s40, 0x14000
	global_load_lds_dwordx4 v227, s[10:11]
	global_load_lds_dwordx4 v227, s[10:11] offset:1024
	s_add_u32 s10, s50, s40
	s_addc_u32 s11, s51, 0
	s_add_u32 m0, m0, 0x2000
	s_nop 0
	global_load_lds_dwordx4 v227, s[10:11]
	global_load_lds_dwordx4 v227, s[10:11] offset:1024
	s_add_u32 s10, s10, 0x2000
	s_addc_u32 s11, s11, 0
	s_add_u32 m0, m0, 0x2000
	s_nop 0
	global_load_lds_dwordx4 v227, s[10:11]
	global_load_lds_dwordx4 v227, s[10:11] offset:1024
	s_add_u32 s10, s10, 0x2000
	s_addc_u32 s11, s11, 0
	s_add_u32 m0, m0, 0x2000
	s_nop 0
	global_load_lds_dwordx4 v227, s[10:11]
	global_load_lds_dwordx4 v227, s[10:11] offset:1024
	s_add_u32 s10, s10, 0x2000
	s_addc_u32 s11, s11, 0
	s_add_u32 m0, m0, 0x2000
	s_nop 0
	global_load_lds_dwordx4 v227, s[10:11]
	global_load_lds_dwordx4 v227, s[10:11] offset:1024
	s_add_i32 s0, s0, 2
	s_mov_b32 s1, 0
	s_mov_b32 s6, 1
	s_waitcnt vmcnt(15)
	s_barrier
	v_add_u32_e32 v225, v135, v138
	v_add_u32_e32 v224, v135, v136
	ds_read_b128 v[144:147], v224
	ds_read_b128 v[152:155], v224 offset:1024
	ds_read_b128 v[180:183], v224 offset:2048
	ds_read_b128 v[140:143], v225 offset:8192
	ds_read_b128 v[148:151], v225 offset:9216
	ds_read_b128 v[156:159], v225 offset:10240
	ds_read_b128 v[160:163], v225 offset:11264
	ds_read_b128 v[164:167], v225 offset:12288
	ds_read_b128 v[168:171], v225 offset:13312
	ds_read_b128 v[172:175], v225 offset:14336
	ds_read_b128 v[176:179], v225 offset:15360
	ds_read_b128 v[184:187], v224 offset:3072

; DI f32x4 mfma16(bf16x8 a, bf16x8 b, f32x4 c) { return __builtin_amdgcn_mfma_f32_16x16x32_bf16(a, b, c, 0, 0, 0); }
; template <int N> DI void wait_vm() { asm volatile("s_waitcnt vmcnt(%0)" ::"n"(N) : "memory"); }
; DI void raw_barrier() { asm volatile("" ::: "memory"); __builtin_amdgcn_s_barrier(); asm volatile("" ::: "memory"); }
;     ...
;     auto compute = [&](int cb, bool do_issue, int ikt, int ib) {
;         const char* base = lds + cb * BUF;
;         bf16x8 af[MT], bfr[NT];
; #pragma unroll
;         for (int nt = 0; nt < NT; ++nt) {
;             const int br = BM + (nt / NTS) * (BN / NSEG) + wc * (NTS * 16) + (nt % NTS) * 16;
;             bfr[nt] = *(const bf16x8*)(base + (br + l15) * 64 + rsw);
;         }
; #pragma unroll
;         for (int mt = 0; mt < MT; ++mt) af[mt] = *(const bf16x8*)(base + (wr * WM + mt * 16 + l15) * 64 + rsw);
;         constexpr int TOT = MT * NT, PER = (TOT + NIT - 1) / NIT;
; #pragma unroll
;         for (int part = 0; part < NIT; ++part) {
; #pragma unroll
;             for (int q = 0; q < PER; ++q) {
;                 const int idx = part * PER + q;
;                 if (idx < TOT) {
;                     const int mt = idx / NT, nt = idx % NT;
;                     acc[mt][nt] = SWAP ? mfma16(bfr[nt], af[mt], acc[mt][nt]) : mfma16(af[mt], bfr[nt], acc[mt][nt]);
;     ...
;     for (int kt = 0; kt < KT; ++kt) {
;         if (D > 1 && kt + D - 1 < KT) wait_vm<(D - 1) * NIT>(); else wait_vm<0>();
;         raw_barrier();
;         compute(cb, kt + D < KT, kt + D, ib);
.Lpx_join:
	s_setprio 0
	s_waitcnt vmcnt(5)
	s_barrier
	v_add_u32_e32 v0, v135, v138
	v_add_u32_e32 v134, v135, v136
	ds_read_b128 v[130:133], v0 offset:8192
	ds_read_b128 v[138:141], v134
	ds_read_b128 v[142:145], v0 offset:9216
	ds_read_b128 v[146:149], v134 offset:1024
	ds_read_b128 v[150:153], v0 offset:10240
	ds_read_b128 v[154:157], v0 offset:11264
	ds_read_b128 v[158:161], v0 offset:12288
	ds_read_b128 v[162:165], v0 offset:13312
	ds_read_b128 v[166:169], v0 offset:14336
	ds_read_b128 v[170:173], v0 offset:15360
	ds_read_b128 v[174:177], v134 offset:2048
	ds_read_b128 v[178:181], v134 offset:3072
	s_waitcnt lgkmcnt(0)
	v_mfma_f32_16x16x32_bf16 v[126:129], v[130:133], v[138:141], v[126:129]
	v_and_b32_e32 v135, 15, v137
	s_lshl_b32 s0, s13, 9
	v_mfma_f32_16x16x32_bf16 v[122:125], v[142:145], v[138:141], v[122:125]
	v_mfma_f32_16x16x32_bf16 v[118:121], v[150:153], v[138:141], v[118:121]
	v_mfma_f32_16x16x32_bf16 v[114:117], v[154:157], v[138:141], v[114:117]
	v_mfma_f32_16x16x32_bf16 v[110:113], v[158:161], v[138:141], v[110:113]
	v_mfma_f32_16x16x32_bf16 v[106:109], v[162:165], v[138:141], v[106:109]
	v_mfma_f32_16x16x32_bf16 v[102:105], v[166:169], v[138:141], v[102:105]
	v_mfma_f32_16x16x32_bf16 v[98:101], v[170:173], v[138:141], v[98:101]
	v_mfma_f32_16x16x32_bf16 v[94:97], v[130:133], v[146:149], v[94:97]
	v_mfma_f32_16x16x32_bf16 v[90:93], v[142:145], v[146:149], v[90:93]
	v_mfma_f32_16x16x32_bf16 v[86:89], v[150:153], v[146:149], v[86:89]
	v_mfma_f32_16x16x32_bf16 v[82:85], v[154:157], v[146:149], v[82:85]
	v_mfma_f32_16x16x32_bf16 v[78:81], v[158:161], v[146:149], v[78:81]
	v_mfma_f32_16x16x32_bf16 v[74:77], v[162:165], v[146:149], v[74:77]
	v_mfma_f32_16x16x32_bf16 v[70:73], v[166:169], v[146:149], v[70:73]
	v_mfma_f32_16x16x32_bf16 v[66:69], v[170:173], v[146:149], v[66:69]
	v_mfma_f32_16x16x32_bf16 v[62:65], v[130:133], v[174:177], v[62:65]
	v_mfma_f32_16x16x32_bf16 v[58:61], v[142:145], v[174:177], v[58:61]
	v_mfma_f32_16x16x32_bf16 v[54:57], v[150:153], v[174:177], v[54:57]
	v_mfma_f32_16x16x32_bf16 v[50:53], v[154:157], v[174:177], v[50:53]
	v_mfma_f32_16x16x32_bf16 v[46:49], v[158:161], v[174:177], v[46:49]
	v_mfma_f32_16x16x32_bf16 v[42:45], v[162:165], v[174:177], v[42:45]
	v_mfma_f32_16x16x32_bf16 v[38:41], v[166:169], v[174:177], v[38:41]
	v_mfma_f32_16x16x32_bf16 v[34:37], v[170:173], v[174:177], v[34:37]
	v_mfma_f32_16x16x32_bf16 v[30:33], v[130:133], v[178:181], v[30:33]
	v_mfma_f32_16x16x32_bf16 v[26:29], v[142:145], v[178:181], v[26:29]
	v_mfma_f32_16x16x32_bf16 v[22:25], v[150:153], v[178:181], v[22:25]
	v_mfma_f32_16x16x32_bf16 v[18:21], v[154:157], v[178:181], v[18:21]
	v_mfma_f32_16x16x32_bf16 v[14:17], v[158:161], v[178:181], v[14:17]
	v_mfma_f32_16x16x32_bf16 v[10:13], v[162:165], v[178:181], v[10:13]
	v_mfma_f32_16x16x32_bf16 v[6:9], v[166:169], v[178:181], v[6:9]
	v_mfma_f32_16x16x32_bf16 v[2:5], v[170:173], v[178:181], v[2:5]
	s_waitcnt vmcnt(0)
	s_barrier
; DI unsigned pk2(float lo, float hi) { const f32x2 v = {lo, hi}; const bf16x2_t b = __builtin_convertvector(v, bf16x2_t); return __builtin_bit_cast(unsigned, b); }
; DI float silu_f(float x) { return x * sigmoid_f(x); }
; DI f32x4 mfma16(bf16x8 a, bf16x8 b, f32x4 c) { return __builtin_amdgcn_mfma_f32_16x16x32_bf16(a, b, c, 0, 0, 0); }
;     ...
;     auto compute = [&](int cb, bool do_issue, int ikt, int ib) {
;         const char* base = lds + cb * BUF;
;         bf16x8 af[MT], bfr[NT];
; #pragma unroll
;         for (int nt = 0; nt < NT; ++nt) {
;             const int br = BM + (nt / NTS) * (BN / NSEG) + wc * (NTS * 16) + (nt % NTS) * 16;
;             bfr[nt] = *(const bf16x8*)(base + (br + l15) * 64 + rsw);
;         }
; #pragma unroll
;         for (int mt = 0; mt < MT; ++mt) af[mt] = *(const bf16x8*)(base + (wr * WM + mt * 16 + l15) * 64 + rsw);
;         constexpr int TOT = MT * NT, PER = (TOT + NIT - 1) / NIT;
; #pragma unroll
;         for (int part = 0; part < NIT; ++part) {
; #pragma unroll
;             for (int q = 0; q < PER; ++q) {
;                 const int idx = part * PER + q;
;                 if (idx < TOT) {
;                     const int mt = idx / NT, nt = idx % NT;
;                     acc[mt][nt] = SWAP ? mfma16(bfr[nt], af[mt], acc[mt][nt]) : mfma16(af[mt], bfr[nt], acc[mt][nt]);
; DI void unit_X(const Params& p, char* lds, int l, int chunk) {
;     ...
; #pragma unroll
;         for (int mt = 0; mt < 4; ++mt) {
;             const int tok = wr * 64 + mt * 16 + l15;
; #pragma unroll
;             for (int nt = 0; nt < 8; ++nt) {
;                 const f32x4 v = acc[mt][nt];
;                 if (wc < 2) {
;                     const int col = wc * 128 + nt * 16 + quad * 4;
;                     const float qs = 0.125f * 1.44269504089f;
;                     *(u32x2*)(Qs + tok * 528 + col * 2) = (u32x2){pk2(v[0] * qs, v[1] * qs), pk2(v[2] * qs, v[3] * qs)};
;                 } else {
;                     const int col = (wc - 2) * 128 + nt * 16 + quad * 4;
;                     *(u32x2*)(gx + (size_t)tok * 256 + col) = (u32x2){pk2(silu_f(v[0]), silu_f(v[1])), pk2(silu_f(v[2]), silu_f(v[3]))};
	ds_read_b128 v[130:133], v0 offset:49152
	ds_read_b128 v[140:143], v0 offset:50176
	ds_read_b128 v[144:147], v134 offset:40960
	ds_read_b128 v[148:151], v134 offset:41984
	ds_read_b128 v[152:155], v0 offset:51200
	ds_read_b128 v[156:159], v0 offset:52224
	ds_read_b128 v[160:163], v0 offset:53248
	ds_read_b128 v[164:167], v0 offset:54272
	ds_read_b128 v[168:171], v0 offset:55296
	ds_read_b128 v[172:175], v0 offset:56320
	ds_read_b128 v[176:179], v134 offset:43008
	ds_read_b128 v[180:183], v134 offset:44032
	s_waitcnt lgkmcnt(0)
	v_mfma_f32_16x16x32_bf16 v[126:129], v[130:133], v[144:147], v[126:129]
	v_readlane_b32 s1, v243, 8
	s_add_u32 s10, s1, s0
	v_readlane_b32 s0, v243, 9
	v_mfma_f32_16x16x32_bf16 v[122:125], v[140:143], v[144:147], v[122:125]
	v_bfe_u32 v138, v137, 6, 2
	v_bfe_u32 v136, v137, 4, 2
	s_addc_u32 s11, s0, 0
	v_mfma_f32_16x16x32_bf16 v[118:121], v[152:155], v[144:147], v[118:121]
	v_mfma_f32_16x16x32_bf16 v[114:117], v[156:159], v[144:147], v[114:117]
	v_mfma_f32_16x16x32_bf16 v[110:113], v[160:163], v[144:147], v[110:113]
	v_mfma_f32_16x16x32_bf16 v[106:109], v[164:167], v[144:147], v[106:109]
	v_mfma_f32_16x16x32_bf16 v[102:105], v[168:171], v[144:147], v[102:105]
	v_mfma_f32_16x16x32_bf16 v[98:101], v[172:175], v[144:147], v[98:101]
	v_mfma_f32_16x16x32_bf16 v[94:97], v[130:133], v[148:151], v[94:97]
	v_mfma_f32_16x16x32_bf16 v[90:93], v[140:143], v[148:151], v[90:93]
	v_mfma_f32_16x16x32_bf16 v[86:89], v[152:155], v[148:151], v[86:89]
	v_mfma_f32_16x16x32_bf16 v[82:85], v[156:159], v[148:151], v[82:85]
	v_mfma_f32_16x16x32_bf16 v[78:81], v[160:163], v[148:151], v[78:81]
	v_mfma_f32_16x16x32_bf16 v[74:77], v[164:167], v[148:151], v[74:77]
	v_mfma_f32_16x16x32_bf16 v[70:73], v[168:171], v[148:151], v[70:73]
	v_mfma_f32_16x16x32_bf16 v[66:69], v[172:175], v[148:151], v[66:69]
	v_mfma_f32_16x16x32_bf16 v[62:65], v[130:133], v[176:179], v[62:65]
	v_mfma_f32_16x16x32_bf16 v[58:61], v[140:143], v[176:179], v[58:61]
	v_mfma_f32_16x16x32_bf16 v[54:57], v[152:155], v[176:179], v[54:57]
	v_mfma_f32_16x16x32_bf16 v[50:53], v[156:159], v[176:179], v[50:53]
	v_mfma_f32_16x16x32_bf16 v[46:49], v[160:163], v[176:179], v[46:49]
	v_mfma_f32_16x16x32_bf16 v[42:45], v[164:167], v[176:179], v[42:45]
	v_mfma_f32_16x16x32_bf16 v[38:41], v[168:171], v[176:179], v[38:41]
	v_mfma_f32_16x16x32_bf16 v[34:37], v[172:175], v[176:179], v[34:37]
	v_mfma_f32_16x16x32_bf16 v[30:33], v[130:133], v[180:183], v[30:33]
	v_mfma_f32_16x16x32_bf16 v[26:29], v[140:143], v[180:183], v[26:29]
	v_mfma_f32_16x16x32_bf16 v[22:25], v[152:155], v[180:183], v[22:25]
	v_mfma_f32_16x16x32_bf16 v[18:21], v[156:159], v[180:183], v[18:21]
	v_mfma_f32_16x16x32_bf16 v[14:17], v[160:163], v[180:183], v[14:17]
	v_mfma_f32_16x16x32_bf16 v[10:13], v[164:167], v[180:183], v[10:13]
	v_mfma_f32_16x16x32_bf16 v[6:9], v[168:171], v[180:183], v[6:9]
	v_mfma_f32_16x16x32_bf16 v[2:5], v[172:175], v[180:183], v[2:5]
	v_ashrrev_i32_e32 v0, 2, v137
	s_movk_i32 s0, 0xffc0
	v_and_or_b32 v130, v0, s0, v135
	v_ashrrev_i32_e32 v131, 31, v130
	v_lshlrev_b32_e32 v0, 7, v138
	v_lshlrev_b32_e32 v134, 2, v136
	v_lshlrev_b64 v[132:133], 9, v[130:131]
	v_cmp_lt_u32_e32 vcc, 1, v138
	v_lshl_add_u64 v[132:133], s[10:11], 0, v[132:133]
	v_add_lshl_u32 v0, v0, v134, 1
	s_waitcnt vmcnt(0)
	s_barrier
	s_and_saveexec_b64 s[0:1], vcc
	s_xor_b64 s[6:7], exec, s[0:1]
	s_cbranch_execz .LBB0_745
	v_mul_f32_e32 v131, 0xbfb8aa3b, v126
	v_exp_f32_e32 v131, v131
	s_nop 0
	v_add_f32_e32 v131, 1.0, v131
	v_rcp_f32_e32 v140, v131
	v_mul_f32_e32 v131, 0xbfb8aa3b, v127
	v_exp_f32_e32 v131, v131
	s_nop 0
	v_add_f32_e32 v131, 1.0, v131
	v_rcp_f32_e32 v141, v131
	s_nop 0
	v_pk_mul_f32 v[126:127], v[126:127], v[140:141]
	s_nop 0
	v_cvt_pk_bf16_f32 v126, v126, v127
	v_mul_f32_e32 v127, 0xbfb8aa3b, v128
	v_exp_f32_e32 v127, v127
	s_nop 0
	v_add_f32_e32 v127, 1.0, v127
	v_rcp_f32_e32 v140, v127
	v_mul_f32_e32 v127, 0xbfb8aa3b, v129
	v_exp_f32_e32 v127, v127
	s_nop 0
	v_add_f32_e32 v127, 1.0, v127
	v_rcp_f32_e32 v141, v127
	s_nop 0
	v_pk_mul_f32 v[128:129], v[128:129], v[140:141]
	s_nop 0
	v_cvt_pk_bf16_f32 v127, v128, v129
	v_lshl_add_u64 v[128:129], v[132:133], 0, v[0:1]
	global_store_dwordx2 v[128:129], v[126:127], off offset:-512

;     ...
;     __syncthreads();
; #pragma unroll
;     for (int d = 0; d < D; ++d) issue(d, d);
; DI void unit_A(const Params& p, char* lds, int l, int chunk, int h) {
;     ...
;     char* WL = lds + 98304;
;     __syncthreads();
;     {
;         const bf16_t* W = WS_PTR(const bf16_t, OFF_WSP) + (size_t)(l * 4 + h) * 16384;
; #pragma unroll
;         for (int i = 0; i < 4; ++i) {
;             const int piece = wid + 8 * i, row = piece * 4 + (lane >> 4), lc = (lane & 15) ^ (row & 15);
;             __builtin_amdgcn_global_load_lds((const unsigned*)(W + row * 128 + lc * 8), (unsigned*)(WL + piece * 1024 + lane * 16), 16, 0, 0);
;         }
;     }
.LBB0_825:
	s_andn2_b64 vcc, exec, s[6:7]
	s_cbranch_vccnz .LBB0_858
	s_ashr_i32 s1, s79, 8
	v_readlane_b32 s6, v242, 23
	s_add_i32 s6, s1, s6
	s_ashr_i32 s7, s6, 31
	s_and_b32 s0, s2, 0xff
	s_lshl_b64 s[8:9], s[6:7], 15
	v_readlane_b32 s7, v244, 40
	v_mov_b32_e32 v191, v212
	s_add_u32 s8, s7, s8
	v_readlane_b32 s7, v244, 41
	s_addc_u32 s9, s7, s9
	v_and_b32_e32 v0, 63, v191
	v_ashrrev_i32_e32 v4, 6, v191
	s_add_i32 s10, 0, 0x18000
	v_bfe_u32 v190, v191, 4, 2
	v_lshl_add_u32 v5, v0, 4, s10
	v_lshlrev_b32_e32 v0, 2, v4
	v_or_b32_e32 v2, v0, v190
	v_bitop3_b32 v0, v0, v191, v190 bitop3:0x36
	v_lshlrev_b32_e32 v2, 7, v2
	v_ashrrev_i32_e32 v3, 31, v2
	v_lshlrev_b32_e32 v0, 4, v0
	v_lshl_add_u64 v[2:3], v[2:3], 1, s[8:9]
	v_and_b32_e32 v0, 0xf0, v0
	v_lshl_add_u64 v[2:3], v[2:3], 0, v[0:1]
	v_lshl_add_u32 v0, v4, 10, v5
	v_add_u32_e32 v6, 8, v4
	v_readfirstlane_b32 s12, v0
	s_mov_b32 m0, s12
	v_lshlrev_b32_e32 v0, 2, v6
	s_barrier
	global_load_lds_dwordx4 v[2:3], off
	v_or_b32_e32 v2, v0, v190
	v_bitop3_b32 v0, v0, v191, v190 bitop3:0x36
	v_lshlrev_b32_e32 v2, 7, v2
	v_ashrrev_i32_e32 v3, 31, v2
	v_lshlrev_b32_e32 v0, 4, v0
	v_lshl_add_u64 v[2:3], v[2:3], 1, s[8:9]
	v_and_b32_e32 v0, 0xf0, v0
	v_lshl_add_u64 v[2:3], v[2:3], 0, v[0:1]
	v_lshl_add_u32 v0, v6, 10, v5
	v_add_u32_e32 v6, 16, v4
	v_readfirstlane_b32 s12, v0
	s_mov_b32 m0, s12
	v_lshlrev_b32_e32 v0, 2, v6
	global_load_lds_dwordx4 v[2:3], off
	v_or_b32_e32 v2, v0, v190
	v_bitop3_b32 v0, v0, v191, v190 bitop3:0x36
	v_lshlrev_b32_e32 v2, 7, v2
	v_ashrrev_i32_e32 v3, 31, v2
	v_lshlrev_b32_e32 v0, 4, v0
	v_lshl_add_u64 v[2:3], v[2:3], 1, s[8:9]
	v_and_b32_e32 v0, 0xf0, v0
	v_lshl_add_u64 v[2:3], v[2:3], 0, v[0:1]
	v_lshl_add_u32 v0, v6, 10, v5
	v_add_u32_e32 v4, 24, v4
	v_readfirstlane_b32 s12, v0
	s_mov_b32 m0, s12
	v_lshlrev_b32_e32 v0, 2, v4
	global_load_lds_dwordx4 v[2:3], off
	v_or_b32_e32 v2, v0, v190
	v_bitop3_b32 v0, v0, v191, v190 bitop3:0x36
	v_lshlrev_b32_e32 v2, 7, v2
	v_ashrrev_i32_e32 v3, 31, v2
	v_lshlrev_b32_e32 v0, 4, v0
	v_lshl_add_u64 v[2:3], v[2:3], 1, s[8:9]
	v_and_b32_e32 v0, 0xf0, v0
	v_lshl_add_u64 v[2:3], v[2:3], 0, v[0:1]
	v_lshl_add_u32 v0, v4, 10, v5
	v_mov_b32_e32 v6, v212
	v_readfirstlane_b32 s8, v0
	s_mov_b32 m0, s8
	s_lshl_b32 s8, s0, 18
	global_load_lds_dwordx4 v[2:3], off
	v_readlane_b32 s9, v243, 56
	v_ashrrev_i32_e32 v7, 6, v6
	v_lshrrev_b32_e32 v0, 30, v7
	v_add_u32_e32 v0, v7, v0
	v_ashrrev_i32_e32 v8, 2, v0
	v_lshrrev_b32_e32 v0, 4, v6
	v_sub_u32_e32 v0, 0, v0
	v_lshlrev_b32_e32 v2, 2, v6
	v_and_b32_e32 v2, 48, v2
	v_xor_b32_e32 v0, v6, v0
	v_lshlrev_b32_e32 v4, 4, v6
	s_add_u32 s14, s9, s8
	v_readlane_b32 s8, v243, 40
	v_sub_u32_e32 v9, 0, v2
	v_and_b32_e32 v2, 0xffffffc0, v4
	v_lshlrev_b32_e32 v0, 4, v0
	s_addc_u32 s15, s8, 0
	s_mul_i32 s8, s1, 0x6000
	v_readlane_b32 s12, v242, 24
	v_and_or_b32 v0, v0, 48, v2
	v_add_u32_e32 v102, 0, v4
	s_mul_hi_i32 s9, s1, 0x6000
	s_add_u32 s8, s12, s8
	v_readlane_b32 s12, v242, 25
	v_lshl_add_u64 v[98:99], s[14:15], 0, v[0:1]
	v_readlane_b32 s14, v243, 25
	v_readfirstlane_b32 s13, v102
	s_addc_u32 s9, s12, s9
	v_readlane_b32 s15, v243, 26
	s_mov_b32 m0, s13
	v_readlane_b32 s13, v243, 4
	v_lshl_add_u64 v[2:3], v[98:99], 0, s[14:15]
	s_add_u32 s14, s8, s13
	v_add_u32_e32 v4, 0x2000, v102
	s_addc_u32 s15, s9, 0
	v_readfirstlane_b32 s13, v4
	v_add_u32_e32 v10, 0x4000, v102
	s_waitcnt vmcnt(0) lgkmcnt(0)
	s_barrier
; template <int N> DI void wait_vm() { asm volatile("s_waitcnt vmcnt(%0)" ::"n"(N) : "memory"); }
; DI void raw_barrier() { asm volatile("" ::: "memory"); __builtin_amdgcn_s_barrier(); asm volatile("" ::: "memory"); }
;     ...
; #pragma unroll
;     for (int mt = 0; mt < MT; ++mt)
; #pragma unroll
;         for (int nt = 0; nt < NT; ++nt) acc[mt][nt] = (f32x4){0.f, 0.f, 0.f, 0.f};
;     const unsigned loff = (unsigned)(lrow * 64 + lcg * 16);
;     const int koff = (int)((blockIdx.x >> 3) + (blockIdx.x & 7) * 4) & (KT - 1);
;     auto issue_one = [&](int kt, int b, int i) {
;         const int row = lrow + 128 * i;
;         if ((NCH % 512 == 0) || (i < NCH / 512) || row < ROWS) {
;             const int kq = (kt + koff) & (KT - 1);
;             const char* ua = (const char*)A + (size_t)((DBG & 1) ? 0 : kq) * (BM * 64);
;             const char* ub = (const char*)Bt + (size_t)((DBG & 2) ? 0 : kq) * ((size_t)ldbk * 2);
;             const char* src;
;             if (BM % 128 == 0) src = (i < BM / 128) ? (ua + i * 8192 + loff) : (ub + (i * 128 - BM) * 64 + loff);
;             else if (i == 0) src = (lrow < BM) ? (ua + loff) : (ub + loff - BM * 64);
;             else src = ub + (i * 128 - BM) * 64 + loff;
;             __builtin_amdgcn_global_load_lds((const unsigned*)src, (unsigned*)(lds + b * BUF + i * 8192 + tid * 16), 16, 0, 0);
;         }
;     };
;     auto issue = [&](int kt, int b) {
; #pragma unroll
;         for (int i = 0; i < NIT; ++i) issue_one(kt, b, i);
;     };
;     auto compute = [&](int cb, bool do_issue, int ikt, int ib) {
;         const char* base = lds + cb * BUF;
;         bf16x8 af[MT], bfr[NT];
; #pragma unroll
;         for (int nt = 0; nt < NT; ++nt) {
;             const int br = BM + (nt / NTS) * (BN / NSEG) + wc * (NTS * 16) + (nt % NTS) * 16;
;             bfr[nt] = *(const bf16x8*)(base + (br + l15) * 64 + rsw);
;         }
; #pragma unroll
;         for (int mt = 0; mt < MT; ++mt) af[mt] = *(const bf16x8*)(base + (wr * WM + mt * 16 + l15) * 64 + rsw);
;     ...
;     __syncthreads();
; #pragma unroll
;     for (int d = 0; d < D; ++d) issue(d, d);
;     int cb = 0, ib = D;
;     for (int kt = 0; kt < KT; ++kt) {
;         if (D > 1 && kt + D - 1 < KT) wait_vm<(D - 1) * NIT>(); else wait_vm<0>();
;         raw_barrier();
;         compute(cb, kt + D < KT, kt + D, ib);
	global_load_lds_dwordx4 v[2:3], off
	v_lshl_add_u64 v[2:3], s[14:15], 0, v[0:1]
	s_mov_b32 m0, s13
	v_readfirstlane_b32 s13, v10
	global_load_lds_dwordx4 v0, s[14:15]
	v_lshl_add_u64 v[4:5], v[2:3], 0, s[76:77]
	s_mov_b32 m0, s13
	v_lshl_add_u64 v[2:3], v[2:3], 0, s[80:81]
	global_load_lds_dwordx4 v[4:5], off
	v_add_u32_e32 v4, 0x6000, v102
	v_readlane_b32 s14, v243, 5
	v_readfirstlane_b32 s13, v4
	v_add_u32_e32 v4, 0x8000, v102
	s_mov_b32 m0, s13
	v_readfirstlane_b32 s13, v4
	global_load_lds_dwordx4 v[2:3], off
	v_readlane_b32 s15, v243, 6
	s_mov_b32 m0, s13
	v_readlane_b32 s13, v243, 7
	v_lshl_add_u64 v[2:3], v[98:99], 0, s[14:15]
	s_add_u32 s14, s8, s13
	v_add_u32_e32 v4, 0xa000, v102
	s_addc_u32 s15, s9, 0
	v_readfirstlane_b32 s13, v4
	v_add_u32_e32 v10, 0xc000, v102
	global_load_lds_dwordx4 v[2:3], off
	v_lshl_add_u64 v[2:3], s[14:15], 0, v[0:1]
	s_mov_b32 m0, s13
	v_readfirstlane_b32 s13, v10
	global_load_lds_dwordx4 v0, s[14:15]
	v_lshl_add_u64 v[4:5], v[2:3], 0, s[76:77]
	s_mov_b32 m0, s13
	v_lshl_add_u64 v[2:3], v[2:3], 0, s[80:81]
	global_load_lds_dwordx4 v[4:5], off
	v_add_u32_e32 v4, 0xe000, v102
	s_mov_b32 s7, 4
	v_readfirstlane_b32 s13, v4
	s_mov_b32 m0, s13
	s_mov_b32 s11, 2
	global_load_lds_dwordx4 v[2:3], off
	v_bitop3_b32 v3, v6, 48, v9 bitop3:0x48
	v_mul_i32_i24_e32 v2, 4, v8
	v_add_u32_e32 v103, 0, v3
	v_lshlrev_b32_e32 v3, 6, v6
	v_sub_u32_e32 v2, v7, v2
	v_and_b32_e32 v3, 0x3c0, v3
	v_lshl_or_b32 v104, v2, 11, v3
	v_mov_b32_e32 v2, 0
	s_mov_b32 s12, 0
	v_lshl_or_b32 v105, v8, 12, v3
	v_lshl_add_u64 v[100:101], s[8:9], 0, v[0:1]
	v_readlane_b32 s13, v243, 24
	v_mov_b32_e32 v3, v2
	v_mov_b32_e32 v4, v2
	v_mov_b32_e32 v5, v2
	v_mov_b32_e32 v6, v2
	v_mov_b32_e32 v7, v2
	v_mov_b32_e32 v8, v2
	v_mov_b32_e32 v9, v2
	v_mov_b32_e32 v10, v2
	v_mov_b32_e32 v11, v2
	v_mov_b32_e32 v12, v2
	v_mov_b32_e32 v13, v2
	v_mov_b32_e32 v14, v2
	v_mov_b32_e32 v15, v2
	v_mov_b32_e32 v16, v2
	v_mov_b32_e32 v17, v2
	v_mov_b32_e32 v18, v2
	v_mov_b32_e32 v19, v2
	v_mov_b32_e32 v20, v2
	v_mov_b32_e32 v21, v2
	v_mov_b32_e32 v22, v2
	v_mov_b32_e32 v23, v2
	v_mov_b32_e32 v24, v2
	v_mov_b32_e32 v25, v2
	v_mov_b32_e32 v26, v2
	v_mov_b32_e32 v27, v2
	v_mov_b32_e32 v28, v2
	v_mov_b32_e32 v29, v2
	v_mov_b32_e32 v30, v2
	v_mov_b32_e32 v31, v2
	v_mov_b32_e32 v32, v2
	v_mov_b32_e32 v33, v2
	v_mov_b32_e32 v34, v2
	v_mov_b32_e32 v35, v2
	v_mov_b32_e32 v36, v2
	v_mov_b32_e32 v37, v2
	v_mov_b32_e32 v38, v2
	v_mov_b32_e32 v39, v2
	v_mov_b32_e32 v40, v2
	v_mov_b32_e32 v41, v2
	v_mov_b32_e32 v42, v2
	v_mov_b32_e32 v43, v2
	v_mov_b32_e32 v44, v2
	v_mov_b32_e32 v45, v2
	v_mov_b32_e32 v46, v2
	v_mov_b32_e32 v47, v2
	v_mov_b32_e32 v48, v2
	v_mov_b32_e32 v49, v2
	v_mov_b32_e32 v50, v2
	v_mov_b32_e32 v51, v2
	v_mov_b32_e32 v52, v2
	v_mov_b32_e32 v53, v2
	v_mov_b32_e32 v54, v2
	v_mov_b32_e32 v55, v2
	v_mov_b32_e32 v56, v2
	v_mov_b32_e32 v57, v2
	v_mov_b32_e32 v58, v2
	v_mov_b32_e32 v59, v2
	v_mov_b32_e32 v60, v2
	v_mov_b32_e32 v61, v2
	v_mov_b32_e32 v62, v2
	v_mov_b32_e32 v63, v2
	v_mov_b32_e32 v64, v2
	v_mov_b32_e32 v65, v2
	v_mov_b32_e32 v66, v2
	v_mov_b32_e32 v67, v2
	v_mov_b32_e32 v68, v2
	v_mov_b32_e32 v69, v2
	v_mov_b32_e32 v70, v2
	v_mov_b32_e32 v71, v2
	v_mov_b32_e32 v72, v2
	v_mov_b32_e32 v73, v2
	v_mov_b32_e32 v74, v2
	v_mov_b32_e32 v75, v2
	v_mov_b32_e32 v76, v2
	v_mov_b32_e32 v77, v2
	v_mov_b32_e32 v78, v2
	v_mov_b32_e32 v79, v2
	v_mov_b32_e32 v80, v2
	v_mov_b32_e32 v81, v2
	v_mov_b32_e32 v82, v2
	v_mov_b32_e32 v83, v2
	v_mov_b32_e32 v84, v2
	v_mov_b32_e32 v85, v2
	v_mov_b32_e32 v86, v2
	v_mov_b32_e32 v87, v2
	v_mov_b32_e32 v88, v2
	v_mov_b32_e32 v89, v2
	v_mov_b32_e32 v90, v2
	v_mov_b32_e32 v91, v2
	v_mov_b32_e32 v92, v2
	v_mov_b32_e32 v93, v2
	v_mov_b32_e32 v94, v2
	v_mov_b32_e32 v95, v2
	v_mov_b32_e32 v96, v2
	v_mov_b32_e32 v97, v2
	v_readfirstlane_b32 s40, v212
	s_nop 3
	s_cmp_lt_u32 s40, 0x100
	s_cbranch_scc0 .Lpa_c_entry
	s_setprio 1
	s_lshl_b32 s13, s40, 5
	s_lshl_b32 s40, s40, 4
	v_add_u32_e32 v227, s40, v0
	v_readfirstlane_b32 s14, v98
	v_readfirstlane_b32 s15, v99
	v_readfirstlane_b32 s40, v0
	s_nop 3
	s_sub_u32 vcc_lo, s14, s40
	s_subb_u32 vcc_hi, s15, 0
	s_mul_i32 s14, s11, 0x8000
	s_add_u32 s14, s14, s13
	s_mov_b32 m0, s14
	s_add_i32 s40, s59, s7
	s_and_b32 s40, s40, 62
	s_lshl_b32 s14, s40, 12
	s_add_u32 s14, vcc_lo, s14
	s_addc_u32 s15, vcc_hi, 0
	s_mul_i32 s40, s40, 0x14000
	global_load_lds_dwordx4 v227, s[14:15]
	global_load_lds_dwordx4 v227, s[14:15] offset:1024
	s_add_u32 s14, s8, s40
	s_addc_u32 s15, s9, 0
	s_add_u32 m0, m0, 0x2000
	s_nop 0
	global_load_lds_dwordx4 v227, s[14:15]
	global_load_lds_dwordx4 v227, s[14:15] offset:1024
	s_add_u32 s14, s14, 0x2000
	s_addc_u32 s15, s15, 0
	s_add_u32 m0, m0, 0x2000
	s_nop 0
	global_load_lds_dwordx4 v227, s[14:15]
	global_load_lds_dwordx4 v227, s[14:15] offset:1024
	s_add_u32 s14, s14, 0x2000
	s_addc_u32 s15, s15, 0
	s_add_u32 m0, m0, 0x2000
	s_nop 0
	global_load_lds_dwordx4 v227, s[14:15]
	global_load_lds_dwordx4 v227, s[14:15] offset:1024
	s_add_i32 s7, s7, 2
	s_mov_b32 s11, 0
	s_mov_b32 s12, 1
	s_waitcnt vmcnt(12)
	s_barrier
	v_add_u32_e32 v225, v103, v104
	v_add_u32_e32 v224, v103, v105
	ds_read_b128 v[106:109], v224
	ds_read_b128 v[118:121], v224 offset:1024
	ds_read_b128 v[138:141], v224 offset:2048
	ds_read_b128 v[110:113], v225 offset:8192
	ds_read_b128 v[114:117], v225 offset:9216
	ds_read_b128 v[122:125], v225 offset:16384
	ds_read_b128 v[126:129], v225 offset:17408
	ds_read_b128 v[130:133], v225 offset:24576
	ds_read_b128 v[134:137], v225 offset:25600
	ds_read_b128 v[142:145], v224 offset:3072

; DI f32x4 mfma16(bf16x8 a, bf16x8 b, f32x4 c) { return __builtin_amdgcn_mfma_f32_16x16x32_bf16(a, b, c, 0, 0, 0); }
; template <int N> DI void wait_vm() { asm volatile("s_waitcnt vmcnt(%0)" ::"n"(N) : "memory"); }
; DI void raw_barrier() { asm volatile("" ::: "memory"); __builtin_amdgcn_s_barrier(); asm volatile("" ::: "memory"); }
;     ...
;     auto compute = [&](int cb, bool do_issue, int ikt, int ib) {
;         const char* base = lds + cb * BUF;
;         bf16x8 af[MT], bfr[NT];
; #pragma unroll
;         for (int nt = 0; nt < NT; ++nt) {
;             const int br = BM + (nt / NTS) * (BN / NSEG) + wc * (NTS * 16) + (nt % NTS) * 16;
;             bfr[nt] = *(const bf16x8*)(base + (br + l15) * 64 + rsw);
;         }
; #pragma unroll
;         for (int mt = 0; mt < MT; ++mt) af[mt] = *(const bf16x8*)(base + (wr * WM + mt * 16 + l15) * 64 + rsw);
;         constexpr int TOT = MT * NT, PER = (TOT + NIT - 1) / NIT;
; #pragma unroll
;         for (int part = 0; part < NIT; ++part) {
; #pragma unroll
;             for (int q = 0; q < PER; ++q) {
;                 const int idx = part * PER + q;
;                 if (idx < TOT) {
;                     const int mt = idx / NT, nt = idx % NT;
;                     acc[mt][nt] = SWAP ? mfma16(bfr[nt], af[mt], acc[mt][nt]) : mfma16(af[mt], bfr[nt], acc[mt][nt]);
;     ...
;     for (int kt = 0; kt < KT; ++kt) {
;         if (D > 1 && kt + D - 1 < KT) wait_vm<(D - 1) * NIT>(); else wait_vm<0>();
;         raw_barrier();
;         compute(cb, kt + D < KT, kt + D, ib);
; DI void unit_A(const Params& p, char* lds, int l, int chunk, int h) {
;     ...
;     for (int n2 = 0; n2 < 2; ++n2) { const int d = wc * 32 + n2 * 16 + l15; lgv[n2] = p.gm_ln_g[(l * 4 + h) * 128 + d]; lbv[n2] = p.gm_ln_b[(l * 4 + h) * 128 + d]; }
;     f32x4 bsv[4];
; #pragma unroll
;     for (int mt = 0; mt < 4; ++mt) bsv[mt] = *(const f32x4*)(p.gm_b_s + (l * 4 + h) * 128 + wr * 64 + mt * 16 + quad * 4);
.Lpa_join:
	s_setprio 0
	s_waitcnt vmcnt(4)
	s_barrier
	v_add_u32_e32 v0, v103, v105
	ds_read_b128 v[98:101], v0
	v_add_u32_e32 v182, v103, v104
	ds_read_b128 v[102:105], v182 offset:8192
	ds_read_b128 v[106:109], v182 offset:9216
	ds_read_b128 v[110:113], v0 offset:1024
	ds_read_b128 v[114:117], v182 offset:16384
	ds_read_b128 v[118:121], v182 offset:17408
	v_bfe_u32 v192, v191, 6, 2
	v_ashrrev_i32_e32 v193, 8, v191
	s_waitcnt lgkmcnt(0)
	v_mfma_f32_16x16x32_bf16 v[122:125], v[98:101], v[118:121], v[82:85]
	s_nop 2
	ds_read_b128 v[82:85], v182 offset:24576
	ds_read_b128 v[126:129], v182 offset:25600
	s_waitcnt lgkmcnt(0)
	v_mfma_f32_16x16x32_bf16 v[130:133], v[98:101], v[82:85], v[78:81]
	s_nop 2
	ds_read_b128 v[78:81], v0 offset:2048
	ds_read_b128 v[134:137], v0 offset:3072
	v_mfma_f32_16x16x32_bf16 v[94:97], v[98:101], v[102:105], v[94:97]
	v_mfma_f32_16x16x32_bf16 v[90:93], v[98:101], v[106:109], v[90:93]
	v_mfma_f32_16x16x32_bf16 v[86:89], v[98:101], v[114:117], v[86:89]
	v_mfma_f32_16x16x32_bf16 v[98:101], v[98:101], v[126:129], v[74:77]
	v_mfma_f32_16x16x32_bf16 v[138:141], v[110:113], v[102:105], v[70:73]
	v_mfma_f32_16x16x32_bf16 v[142:145], v[110:113], v[106:109], v[66:69]
	v_mfma_f32_16x16x32_bf16 v[146:149], v[110:113], v[114:117], v[62:65]
	v_mfma_f32_16x16x32_bf16 v[150:153], v[110:113], v[118:121], v[58:61]
	v_mfma_f32_16x16x32_bf16 v[54:57], v[110:113], v[82:85], v[54:57]
	v_mfma_f32_16x16x32_bf16 v[110:113], v[110:113], v[126:129], v[50:53]
	s_waitcnt lgkmcnt(0)
	v_mfma_f32_16x16x32_bf16 v[154:157], v[78:81], v[102:105], v[46:49]
	v_mfma_f32_16x16x32_bf16 v[158:161], v[78:81], v[106:109], v[42:45]
	v_mfma_f32_16x16x32_bf16 v[162:165], v[78:81], v[114:117], v[38:41]
	v_mfma_f32_16x16x32_bf16 v[34:37], v[78:81], v[118:121], v[34:37]
	v_mfma_f32_16x16x32_bf16 v[166:169], v[78:81], v[82:85], v[30:33]
	v_mfma_f32_16x16x32_bf16 v[76:79], v[78:81], v[126:129], v[26:29]
	v_mfma_f32_16x16x32_bf16 v[102:105], v[134:137], v[102:105], v[22:25]
	v_mfma_f32_16x16x32_bf16 v[106:109], v[134:137], v[106:109], v[18:21]
	v_mfma_f32_16x16x32_bf16 v[14:17], v[134:137], v[114:117], v[14:17]
	v_mfma_f32_16x16x32_bf16 v[114:117], v[134:137], v[118:121], v[10:13]
	v_mfma_f32_16x16x32_bf16 v[118:121], v[134:137], v[82:85], v[6:9]
	v_mfma_f32_16x16x32_bf16 v[2:5], v[134:137], v[126:129], v[2:5]
	s_waitcnt vmcnt(0)
	s_barrier
	s_nop 0
	ds_read_b128 v[6:9], v0 offset:32768
	ds_read_b128 v[10:13], v182 offset:40960
	ds_read_b128 v[126:129], v182 offset:41984
	ds_read_b128 v[18:21], v0 offset:33792
	ds_read_b128 v[134:137], v182 offset:49152
	ds_read_b128 v[170:173], v182 offset:50176
	s_waitcnt lgkmcnt(0)
	v_mfma_f32_16x16x32_bf16 v[174:177], v[6:9], v[134:137], v[86:89]
	v_and_b32_e32 v194, 15, v191
	v_mfma_f32_16x16x32_bf16 v[178:181], v[6:9], v[170:173], v[122:125]
	s_nop 0
	ds_read_b128 v[84:87], v182 offset:57344
	s_nop 0
	ds_read_b128 v[122:125], v182 offset:58368
	s_waitcnt lgkmcnt(0)
	v_mfma_f32_16x16x32_bf16 v[72:75], v[6:9], v[84:87], v[130:133]
	ds_read_b128 v[22:25], v0 offset:34816
	s_nop 1
	ds_read_b128 v[130:133], v0 offset:35840
	v_mfma_f32_16x16x32_bf16 v[80:83], v[6:9], v[10:13], v[94:97]
	v_mfma_f32_16x16x32_bf16 v[68:71], v[6:9], v[126:129], v[90:93]
	v_mfma_f32_16x16x32_bf16 v[64:67], v[6:9], v[122:125], v[98:101]
	v_mfma_f32_16x16x32_bf16 v[60:63], v[18:21], v[10:13], v[138:141]
	v_mfma_f32_16x16x32_bf16 v[48:51], v[18:21], v[126:129], v[142:145]
	v_mfma_f32_16x16x32_bf16 v[182:185], v[18:21], v[134:137], v[146:149]
	v_mfma_f32_16x16x32_bf16 v[186:189], v[18:21], v[170:173], v[150:153]
	v_mfma_f32_16x16x32_bf16 v[52:55], v[18:21], v[84:87], v[54:57]
	v_mfma_f32_16x16x32_bf16 v[44:47], v[18:21], v[122:125], v[110:113]
	s_waitcnt lgkmcnt(0)
	v_mfma_f32_16x16x32_bf16 v[40:43], v[22:25], v[10:13], v[154:157]
	v_mfma_f32_16x16x32_bf16 v[28:31], v[22:25], v[126:129], v[158:161]
	v_mfma_f32_16x16x32_bf16 v[96:99], v[22:25], v[134:137], v[162:165]
	v_mfma_f32_16x16x32_bf16 v[92:95], v[22:25], v[170:173], v[34:37]
	v_mfma_f32_16x16x32_bf16 v[32:35], v[22:25], v[84:87], v[166:169]
	v_mfma_f32_16x16x32_bf16 v[24:27], v[22:25], v[122:125], v[76:79]
	v_mfma_f32_16x16x32_bf16 v[20:23], v[130:133], v[10:13], v[102:105]
	v_mfma_f32_16x16x32_bf16 v[8:11], v[130:133], v[126:129], v[106:109]
	v_mfma_f32_16x16x32_bf16 v[88:91], v[130:133], v[134:137], v[14:17]
	v_mfma_f32_16x16x32_bf16 v[76:79], v[130:133], v[170:173], v[114:117]
	v_mfma_f32_16x16x32_bf16 v[12:15], v[130:133], v[84:87], v[118:121]
	v_mfma_f32_16x16x32_bf16 v[4:7], v[130:133], v[122:125], v[2:5]
	s_lshl_b32 s6, s6, 7
	s_nop 1
	v_lshl_or_b32 v3, v192, 5, v194
	v_or_b32_e32 v16, s6, v3
	s_ashr_i32 s7, s6, 31
	v_ashrrev_i32_e32 v17, 31, v16
	s_lshl_b64 s[6:7], s[6:7], 2
	v_lshlrev_b64 v[16:17], 2, v[16:17]
	s_add_u32 s6, s60, s6
	v_lshlrev_b32_e32 v124, 6, v193
	v_lshl_add_u64 v[18:19], s[62:63], 0, v[16:17]
	v_lshl_add_u64 v[16:17], s[64:65], 0, v[16:17]
	s_addc_u32 s7, s61, s7
	v_ashrrev_i32_e32 v125, 31, v124
	s_waitcnt vmcnt(0)
	s_barrier
; DI void unit_A(const Params& p, char* lds, int l, int chunk, int h) {
;     ...
;     for (int n2 = 0; n2 < 2; ++n2) { const int d = wc * 32 + n2 * 16 + l15; lgv[n2] = p.gm_ln_g[(l * 4 + h) * 128 + d]; lbv[n2] = p.gm_ln_b[(l * 4 + h) * 128 + d]; }
;     f32x4 bsv[4];
; #pragma unroll
;     for (int mt = 0; mt < 4; ++mt) bsv[mt] = *(const f32x4*)(p.gm_b_s + (l * 4 + h) * 128 + wr * 64 + mt * 16 + quad * 4);
;     {
;         float sv[4][4], ssv[4][4];
; #pragma unroll
;         for (int mt = 0; mt < 4; ++mt)
; #pragma unroll
;             for (int i = 0; i < 4; ++i) {
;                 float s = 0.f, ss = 0.f;
; #pragma unroll
;                 for (int n2 = 0; n2 < 2; ++n2) { const float v = gelu_f(acc[mt][2 + n2][i]); acc[mt][2 + n2][i] = v; s += v; ss += v * v; }
;                 sv[mt][i] = s; ssv[mt][i] = ss;
	global_load_dword v102, v[18:19], off
	global_load_dword v2, v[18:19], off offset:64
	global_load_dword v104, v[16:17], off
	global_load_dword v100, v[16:17], off offset:64
	v_lshl_add_u64 v[16:17], v[124:125], 2, s[6:7]
	v_lshlrev_b32_e32 v0, 4, v190
	v_lshl_add_u64 v[16:17], v[16:17], 0, v[0:1]
	v_mul_f32_e32 v0, v174, v174
	v_fmamk_f32 v0, v0, 0xbdd2d3e8, v213
	v_mul_f32_e32 v103, v178, v178
	v_mul_f32_e32 v0, v174, v0
	v_fmamk_f32 v103, v103, 0xbdd2d3e8, v213
	v_mul_f32_e32 v105, v175, v175
	v_exp_f32_e32 v0, v0
	v_mul_f32_e32 v103, v178, v103
	v_fmamk_f32 v105, v105, 0xbdd2d3e8, v213
	v_exp_f32_e32 v103, v103
	v_mul_f32_e32 v105, v175, v105
	v_exp_f32_e32 v105, v105
	v_add_f32_e32 v0, 1.0, v0
	v_rcp_f32_e32 v106, v0
	v_add_f32_e32 v0, 1.0, v103
	v_rcp_f32_e32 v108, v0
	v_add_f32_e32 v0, 1.0, v105
	v_rcp_f32_e32 v107, v0
	v_mul_f32_e32 v0, v179, v179
	v_fmamk_f32 v0, v0, 0xbdd2d3e8, v213
	v_mul_f32_e32 v0, v179, v0
	v_exp_f32_e32 v0, v0
	v_mul_f32_e32 v103, v180, v180
	v_fmamk_f32 v103, v103, 0xbdd2d3e8, v213
	v_mul_f32_e32 v105, v177, v177
	v_add_f32_e32 v0, 1.0, v0
	v_rcp_f32_e32 v109, v0
	v_mul_f32_e32 v0, v176, v176
	v_fmamk_f32 v0, v0, 0xbdd2d3e8, v213
	v_mul_f32_e32 v0, v176, v0
	v_exp_f32_e32 v0, v0
	v_mul_f32_e32 v103, v180, v103
	v_fmamk_f32 v105, v105, 0xbdd2d3e8, v213
	v_exp_f32_e32 v103, v103
	v_mul_f32_e32 v105, v177, v105
	v_exp_f32_e32 v105, v105
	v_add_f32_e32 v0, 1.0, v0
	v_pk_mul_f32 v[116:117], v[174:175], v[106:107]
	v_rcp_f32_e32 v106, v0
	v_add_f32_e32 v0, 1.0, v103
	v_pk_mul_f32 v[114:115], v[178:179], v[108:109]
	v_rcp_f32_e32 v108, v0
	v_add_f32_e32 v0, 1.0, v105
	v_rcp_f32_e32 v107, v0
	v_mul_f32_e32 v0, v181, v181
	v_fmamk_f32 v0, v0, 0xbdd2d3e8, v213
	v_mul_f32_e32 v0, v181, v0
	v_exp_f32_e32 v0, v0
	v_mul_f32_e32 v103, v186, v186
	v_fmamk_f32 v103, v103, 0xbdd2d3e8, v213
	v_mul_f32_e32 v105, v183, v183
	v_add_f32_e32 v0, 1.0, v0
	v_rcp_f32_e32 v109, v0
	v_mul_f32_e32 v0, v182, v182
	v_fmamk_f32 v0, v0, 0xbdd2d3e8, v213
	v_mul_f32_e32 v0, v182, v0
	v_exp_f32_e32 v0, v0
	v_mul_f32_e32 v103, v186, v103
	v_fmamk_f32 v105, v105, 0xbdd2d3e8, v213
	v_exp_f32_e32 v103, v103
	v_mul_f32_e32 v105, v183, v105
	v_exp_f32_e32 v105, v105
	v_add_f32_e32 v0, 1.0, v0
	v_pk_mul_f32 v[118:119], v[176:177], v[106:107]
	v_rcp_f32_e32 v106, v0
	v_add_f32_e32 v0, 1.0, v103
	v_rcp_f32_e32 v110, v0
	v_add_f32_e32 v0, 1.0, v105
	v_rcp_f32_e32 v107, v0
	v_mul_f32_e32 v0, v187, v187
	v_fmamk_f32 v0, v0, 0xbdd2d3e8, v213
	v_mul_f32_e32 v0, v187, v0
	v_exp_f32_e32 v0, v0
	v_mul_f32_e32 v103, v188, v188
	v_fmamk_f32 v103, v103, 0xbdd2d3e8, v213
	v_mul_f32_e32 v105, v185, v185
	v_add_f32_e32 v0, 1.0, v0
	v_rcp_f32_e32 v111, v0
	v_mul_f32_e32 v0, v184, v184
	v_fmamk_f32 v0, v0, 0xbdd2d3e8, v213
	v_mul_f32_e32 v0, v184, v0
	v_exp_f32_e32 v0, v0
	v_mul_f32_e32 v103, v188, v103
	v_fmamk_f32 v105, v105, 0xbdd2d3e8, v213
	v_exp_f32_e32 v103, v103
	v_mul_f32_e32 v105, v185, v105
	v_exp_f32_e32 v105, v105
	v_add_f32_e32 v0, 1.0, v0
	v_pk_mul_f32 v[120:121], v[180:181], v[108:109]
	v_pk_mul_f32 v[108:109], v[182:183], v[106:107]
	v_pk_mul_f32 v[106:107], v[186:187], v[110:111]
	v_rcp_f32_e32 v110, v0
	v_add_f32_e32 v0, 1.0, v103
	v_rcp_f32_e32 v112, v0
	v_add_f32_e32 v0, 1.0, v105
	v_rcp_f32_e32 v111, v0
	v_mul_f32_e32 v0, v189, v189
	v_fmamk_f32 v0, v0, 0xbdd2d3e8, v213
	v_mul_f32_e32 v0, v189, v0
	v_exp_f32_e32 v0, v0
	v_mul_f32_e32 v103, v92, v92
	v_fmamk_f32 v103, v103, 0xbdd2d3e8, v213
	v_mul_f32_e32 v105, v97, v97
	v_add_f32_e32 v0, 1.0, v0
	v_rcp_f32_e32 v113, v0
	v_mul_f32_e32 v0, v96, v96
	v_fmamk_f32 v0, v0, 0xbdd2d3e8, v213
	v_mul_f32_e32 v0, v96, v0
	v_exp_f32_e32 v0, v0
	v_mul_f32_e32 v103, v92, v103
	v_fmamk_f32 v105, v105, 0xbdd2d3e8, v213
	global_load_dwordx4 v[84:87], v[16:17], off
	global_load_dwordx4 v[56:59], v[16:17], off offset:64
	global_load_dwordx4 v[36:39], v[16:17], off offset:128
	s_nop 0
	global_load_dwordx4 v[16:19], v[16:17], off offset:192
	v_exp_f32_e32 v103, v103
	v_mul_f32_e32 v105, v97, v105
	v_exp_f32_e32 v105, v105
	v_add_f32_e32 v0, 1.0, v0
	v_rcp_f32_e32 v126, v0
	v_add_f32_e32 v0, 1.0, v103
	v_rcp_f32_e32 v160, v0
	v_add_f32_e32 v0, 1.0, v105
	v_rcp_f32_e32 v127, v0
	v_mul_f32_e32 v0, v93, v93
	v_fmamk_f32 v0, v0, 0xbdd2d3e8, v213
	v_mul_f32_e32 v0, v93, v0
	v_exp_f32_e32 v0, v0
	v_mul_f32_e32 v103, v94, v94
	v_fmamk_f32 v103, v103, 0xbdd2d3e8, v213
	v_mul_f32_e32 v105, v99, v99
	v_add_f32_e32 v0, 1.0, v0
	v_rcp_f32_e32 v161, v0
	v_mul_f32_e32 v0, v98, v98
	v_fmamk_f32 v0, v0, 0xbdd2d3e8, v213
	v_mul_f32_e32 v0, v98, v0
	v_exp_f32_e32 v0, v0
	v_mul_f32_e32 v103, v94, v103
	v_fmamk_f32 v105, v105, 0xbdd2d3e8, v213
	v_exp_f32_e32 v103, v103
	v_mul_f32_e32 v105, v99, v105
	v_exp_f32_e32 v105, v105
	v_add_f32_e32 v0, 1.0, v0
	v_pk_mul_f32 v[96:97], v[96:97], v[126:127]
	v_rcp_f32_e32 v126, v0
	v_add_f32_e32 v0, 1.0, v103
	v_pk_mul_f32 v[92:93], v[92:93], v[160:161]
	v_rcp_f32_e32 v160, v0
	v_add_f32_e32 v0, 1.0, v105
	v_rcp_f32_e32 v127, v0
	v_mul_f32_e32 v0, v95, v95
	v_fmamk_f32 v0, v0, 0xbdd2d3e8, v213
	v_mul_f32_e32 v0, v95, v0
	v_exp_f32_e32 v0, v0
	v_mul_f32_e32 v103, v76, v76
	v_fmamk_f32 v103, v103, 0xbdd2d3e8, v213
	v_mul_f32_e32 v105, v89, v89
	v_add_f32_e32 v0, 1.0, v0
	v_rcp_f32_e32 v161, v0
	v_mul_f32_e32 v0, v88, v88
	v_fmamk_f32 v0, v0, 0xbdd2d3e8, v213
	v_mul_f32_e32 v0, v88, v0
	v_exp_f32_e32 v0, v0
	v_mul_f32_e32 v103, v76, v103
	v_fmamk_f32 v105, v105, 0xbdd2d3e8, v213
	v_exp_f32_e32 v103, v103
	v_mul_f32_e32 v105, v89, v105
	v_exp_f32_e32 v105, v105
	v_add_f32_e32 v0, 1.0, v0
	v_pk_mul_f32 v[98:99], v[98:99], v[126:127]
	v_rcp_f32_e32 v126, v0
	v_add_f32_e32 v0, 1.0, v103
; template <int CTRL> DI float dpp_f(float v) { return __builtin_bit_cast(float, __builtin_amdgcn_update_dpp(0, __builtin_bit_cast(int, v), CTRL, 0xF, 0xF, true)); }
; DI float row16_sum(float v) {
;     v += dpp_f<0xB1>(v);
;     v += dpp_f<0x4E>(v);
;     v += dpp_f<0x141>(v);
;     v += dpp_f<0x140>(v);
;     return v;
; }
; DI void unit_A(const Params& p, char* lds, int l, int chunk, int h) {
;     ...
;                 for (int n2 = 0; n2 < 2; ++n2) { const float v = gelu_f(acc[mt][2 + n2][i]); acc[mt][2 + n2][i] = v; s += v; ss += v * v; }
;                 sv[mt][i] = s; ssv[mt][i] = ss;
;             }
; #pragma unroll
;         for (int mt = 0; mt < 4; ++mt)
; #pragma unroll
;             for (int i = 0; i < 4; ++i) { sv[mt][i] = row16_sum(sv[mt][i]); ssv[mt][i] = row16_sum(ssv[mt][i]); }
	v_pk_mul_f32 v[94:95], v[94:95], v[160:161]
	v_rcp_f32_e32 v160, v0
	v_add_f32_e32 v0, 1.0, v105
	v_rcp_f32_e32 v127, v0
	v_mul_f32_e32 v0, v77, v77
	v_fmamk_f32 v0, v0, 0xbdd2d3e8, v213
	v_mul_f32_e32 v0, v77, v0
	v_exp_f32_e32 v0, v0
	v_mul_f32_e32 v103, v91, v91
	v_fmamk_f32 v103, v103, 0xbdd2d3e8, v213
	v_mul_f32_e32 v103, v91, v103
	v_add_f32_e32 v0, 1.0, v0
	v_rcp_f32_e32 v161, v0
	v_mul_f32_e32 v0, v90, v90
	v_fmamk_f32 v0, v0, 0xbdd2d3e8, v213
	v_mul_f32_e32 v0, v90, v0
	v_exp_f32_e32 v0, v0
	v_exp_f32_e32 v103, v103
	v_pk_mul_f32 v[88:89], v[88:89], v[126:127]
	v_pk_mul_f32 v[128:129], v[116:117], v[116:117]
	v_add_f32_e32 v0, 1.0, v0
	v_rcp_f32_e32 v126, v0
	v_mul_f32_e32 v0, v78, v78
	v_add_f32_e32 v103, 1.0, v103
	v_fmamk_f32 v0, v0, 0xbdd2d3e8, v213
	v_rcp_f32_e32 v127, v103
	v_mul_f32_e32 v103, v79, v79
	v_mul_f32_e32 v0, v78, v0
	v_fmamk_f32 v103, v103, 0xbdd2d3e8, v213
	v_exp_f32_e32 v0, v0
	v_mul_f32_e32 v103, v79, v103
	v_exp_f32_e32 v103, v103
	v_pk_mul_f32 v[132:133], v[114:115], v[114:115]
	v_add_f32_e32 v0, 1.0, v0
	v_add_f32_e32 v130, 0, v117
	v_pk_mul_f32 v[136:137], v[118:119], v[118:119]
	v_pk_mul_f32 v[140:141], v[120:121], v[120:121]
	v_rcp_f32_e32 v170, v0
	v_pk_mul_f32 v[90:91], v[90:91], v[126:127]
	v_add_f32_e32 v0, 1.0, v103
	v_mov_b32_e32 v127, v132
	v_mov_b32_e32 v131, v129
	v_mov_b32_e32 v132, v115
	v_add_f32_e32 v138, 0, v119
	v_pk_mul_f32 v[144:145], v[108:109], v[108:109]
	v_pk_mul_f32 v[148:149], v[106:107], v[106:107]
	v_pk_mul_f32 v[110:111], v[184:185], v[110:111]
	v_pk_mul_f32 v[112:113], v[188:189], v[112:113]
	v_rcp_f32_e32 v171, v0
	v_mov_b32_e32 v123, v128
	v_pk_add_f32 v[128:129], v[130:131], v[132:133]
	v_mov_b32_e32 v133, v140
	v_mov_b32_e32 v139, v137
	v_mov_b32_e32 v140, v121
	v_add_f32_e32 v146, 0, v109
	v_pk_mul_f32 v[152:153], v[110:111], v[110:111]
	v_pk_mul_f32 v[156:157], v[112:113], v[112:113]
	v_mov_b32_e32 v135, v136
	v_pk_add_f32 v[136:137], v[138:139], v[140:141]
	v_mov_b32_e32 v141, v148
	v_mov_b32_e32 v147, v145
	v_mov_b32_e32 v148, v107
	v_add_f32_e32 v154, 0, v111
	v_pk_mul_f32 v[168:169], v[96:97], v[96:97]
	v_pk_mul_f32 v[182:183], v[92:93], v[92:93]
	v_mov_b32_e32 v143, v144
	v_pk_add_f32 v[144:145], v[146:147], v[148:149]
	v_mov_b32_e32 v149, v156
	v_mov_b32_e32 v155, v153
	v_mov_b32_e32 v156, v113
	v_add_f32_e32 v178, 0, v97
	v_pk_mul_f32 v[164:165], v[98:99], v[98:99]
	v_pk_mul_f32 v[180:181], v[94:95], v[94:95]
	v_pk_mul_f32 v[76:77], v[76:77], v[160:161]
	v_mov_b32_e32 v151, v152
	v_pk_add_f32 v[152:153], v[154:155], v[156:157]
	v_mov_b32_e32 v157, v182
	v_mov_b32_e32 v179, v169
	v_mov_b32_e32 v182, v93
	v_add_f32_e32 v176, 0, v99
	v_pk_mul_f32 v[162:163], v[88:89], v[88:89]
	v_pk_mul_f32 v[174:175], v[76:77], v[76:77]
	v_pk_mul_f32 v[78:79], v[78:79], v[170:171]
	v_mov_b32_e32 v159, v168
	v_pk_add_f32 v[168:169], v[178:179], v[182:183]
	v_mov_b32_e32 v183, v180
	v_mov_b32_e32 v177, v165
	v_mov_b32_e32 v180, v95
	v_add_f32_e32 v172, 0, v89
	v_pk_mul_f32 v[166:167], v[90:91], v[90:91]
	v_pk_mul_f32 v[170:171], v[78:79], v[78:79]
	v_mov_b32_e32 v189, v164
	v_pk_add_f32 v[164:165], v[176:177], v[180:181]
	v_mov_b32_e32 v181, v174
	v_mov_b32_e32 v173, v163
	v_mov_b32_e32 v174, v77
	v_add_f32_e32 v122, 0, v116
	v_add_f32_e32 v134, 0, v118
	v_add_f32_e32 v142, 0, v108
	v_add_f32_e32 v150, 0, v110
	v_add_f32_e32 v158, 0, v96
	v_add_f32_e32 v188, 0, v98
	v_add_f32_e32 v184, 0, v88
	v_add_f32_e32 v186, 0, v90
	v_add_f32_e32 v160, 0, v91
	v_mov_b32_e32 v126, v114
	v_mov_b32_e32 v132, v120
	v_mov_b32_e32 v140, v106
	v_mov_b32_e32 v148, v112
	v_mov_b32_e32 v156, v92
	v_mov_b32_e32 v182, v94
	v_mov_b32_e32 v185, v162
	v_mov_b32_e32 v180, v76
	v_pk_add_f32 v[162:163], v[172:173], v[174:175]
	v_mov_b32_e32 v187, v166
	v_mov_b32_e32 v174, v78
	v_mov_b32_e32 v175, v170
	v_mov_b32_e32 v161, v167
	v_mov_b32_e32 v170, v79
	v_pk_add_f32 v[122:123], v[122:123], v[126:127]
	v_pk_add_f32 v[132:133], v[134:135], v[132:133]
	v_pk_add_f32 v[140:141], v[142:143], v[140:141]
	v_pk_add_f32 v[148:149], v[150:151], v[148:149]
	v_pk_add_f32 v[156:157], v[158:159], v[156:157]
	v_pk_add_f32 v[182:183], v[188:189], v[182:183]
	v_pk_add_f32 v[180:181], v[184:185], v[180:181]
	v_pk_add_f32 v[174:175], v[186:187], v[174:175]
	v_pk_add_f32 v[160:161], v[160:161], v[170:171]
	v_mov_b32_dpp v126, v122 quad_perm:[1,0,3,2] row_mask:0xf bank_mask:0xf bound_ctrl:1
	v_mov_b32_dpp v127, v123 quad_perm:[1,0,3,2] row_mask:0xf bank_mask:0xf bound_ctrl:1
	v_mov_b32_dpp v130, v128 quad_perm:[1,0,3,2] row_mask:0xf bank_mask:0xf bound_ctrl:1
	v_mov_b32_dpp v131, v129 quad_perm:[1,0,3,2] row_mask:0xf bank_mask:0xf bound_ctrl:1
	v_mov_b32_dpp v134, v132 quad_perm:[1,0,3,2] row_mask:0xf bank_mask:0xf bound_ctrl:1
	v_mov_b32_dpp v135, v133 quad_perm:[1,0,3,2] row_mask:0xf bank_mask:0xf bound_ctrl:1
	v_mov_b32_dpp v138, v136 quad_perm:[1,0,3,2] row_mask:0xf bank_mask:0xf bound_ctrl:1
	v_mov_b32_dpp v139, v137 quad_perm:[1,0,3,2] row_mask:0xf bank_mask:0xf bound_ctrl:1
	v_mov_b32_dpp v142, v140 quad_perm:[1,0,3,2] row_mask:0xf bank_mask:0xf bound_ctrl:1
	v_mov_b32_dpp v143, v141 quad_perm:[1,0,3,2] row_mask:0xf bank_mask:0xf bound_ctrl:1
	v_mov_b32_dpp v146, v144 quad_perm:[1,0,3,2] row_mask:0xf bank_mask:0xf bound_ctrl:1
	v_mov_b32_dpp v147, v145 quad_perm:[1,0,3,2] row_mask:0xf bank_mask:0xf bound_ctrl:1
	v_mov_b32_dpp v150, v148 quad_perm:[1,0,3,2] row_mask:0xf bank_mask:0xf bound_ctrl:1
	v_mov_b32_dpp v151, v149 quad_perm:[1,0,3,2] row_mask:0xf bank_mask:0xf bound_ctrl:1
	v_mov_b32_dpp v154, v152 quad_perm:[1,0,3,2] row_mask:0xf bank_mask:0xf bound_ctrl:1
	v_mov_b32_dpp v155, v153 quad_perm:[1,0,3,2] row_mask:0xf bank_mask:0xf bound_ctrl:1
; template <int CTRL> DI float dpp_f(float v) { return __builtin_bit_cast(float, __builtin_amdgcn_update_dpp(0, __builtin_bit_cast(int, v), CTRL, 0xF, 0xF, true)); }
; DI float row16_sum(float v) {
;     v += dpp_f<0xB1>(v);
;     v += dpp_f<0x4E>(v);
;     v += dpp_f<0x141>(v);
;     v += dpp_f<0x140>(v);
;     return v;
; }
; DI void unit_A(const Params& p, char* lds, int l, int chunk, int h) {
;     ...
;             for (int i = 0; i < 4; ++i) { sv[mt][i] = row16_sum(sv[mt][i]); ssv[mt][i] = row16_sum(ssv[mt][i]); }
	v_mov_b32_dpp v158, v156 quad_perm:[1,0,3,2] row_mask:0xf bank_mask:0xf bound_ctrl:1
	v_mov_b32_dpp v159, v157 quad_perm:[1,0,3,2] row_mask:0xf bank_mask:0xf bound_ctrl:1
	v_mov_b32_dpp v178, v168 quad_perm:[1,0,3,2] row_mask:0xf bank_mask:0xf bound_ctrl:1
	v_mov_b32_dpp v179, v169 quad_perm:[1,0,3,2] row_mask:0xf bank_mask:0xf bound_ctrl:1
	v_mov_b32_dpp v188, v182 quad_perm:[1,0,3,2] row_mask:0xf bank_mask:0xf bound_ctrl:1
	v_mov_b32_dpp v189, v183 quad_perm:[1,0,3,2] row_mask:0xf bank_mask:0xf bound_ctrl:1
	v_mov_b32_dpp v176, v164 quad_perm:[1,0,3,2] row_mask:0xf bank_mask:0xf bound_ctrl:1
	v_mov_b32_dpp v177, v165 quad_perm:[1,0,3,2] row_mask:0xf bank_mask:0xf bound_ctrl:1
	v_mov_b32_dpp v184, v180 quad_perm:[1,0,3,2] row_mask:0xf bank_mask:0xf bound_ctrl:1
	v_mov_b32_dpp v185, v181 quad_perm:[1,0,3,2] row_mask:0xf bank_mask:0xf bound_ctrl:1
	v_mov_b32_dpp v172, v162 quad_perm:[1,0,3,2] row_mask:0xf bank_mask:0xf bound_ctrl:1
	v_mov_b32_dpp v173, v163 quad_perm:[1,0,3,2] row_mask:0xf bank_mask:0xf bound_ctrl:1
	v_mov_b32_dpp v186, v174 quad_perm:[1,0,3,2] row_mask:0xf bank_mask:0xf bound_ctrl:1
	v_mov_b32_dpp v187, v175 quad_perm:[1,0,3,2] row_mask:0xf bank_mask:0xf bound_ctrl:1
	v_mov_b32_dpp v166, v160 quad_perm:[1,0,3,2] row_mask:0xf bank_mask:0xf bound_ctrl:1
	v_mov_b32_dpp v167, v161 quad_perm:[1,0,3,2] row_mask:0xf bank_mask:0xf bound_ctrl:1
	v_pk_add_f32 v[122:123], v[122:123], v[126:127]
	v_pk_add_f32 v[128:129], v[128:129], v[130:131]
	v_pk_add_f32 v[132:133], v[132:133], v[134:135]
	v_pk_add_f32 v[136:137], v[136:137], v[138:139]
	v_pk_add_f32 v[140:141], v[140:141], v[142:143]
	v_pk_add_f32 v[144:145], v[144:145], v[146:147]
	v_pk_add_f32 v[148:149], v[148:149], v[150:151]
	v_pk_add_f32 v[152:153], v[152:153], v[154:155]
	v_pk_add_f32 v[156:157], v[156:157], v[158:159]
	v_pk_add_f32 v[168:169], v[168:169], v[178:179]
	v_pk_add_f32 v[182:183], v[182:183], v[188:189]
	v_pk_add_f32 v[164:165], v[164:165], v[176:177]
	v_pk_add_f32 v[180:181], v[180:181], v[184:185]
	v_pk_add_f32 v[162:163], v[162:163], v[172:173]
	v_pk_add_f32 v[174:175], v[174:175], v[186:187]
	v_pk_add_f32 v[160:161], v[160:161], v[166:167]
	v_mov_b32_dpp v126, v122 quad_perm:[2,3,0,1] row_mask:0xf bank_mask:0xf bound_ctrl:1
	v_mov_b32_dpp v127, v123 quad_perm:[2,3,0,1] row_mask:0xf bank_mask:0xf bound_ctrl:1
	v_mov_b32_dpp v130, v128 quad_perm:[2,3,0,1] row_mask:0xf bank_mask:0xf bound_ctrl:1
	v_mov_b32_dpp v131, v129 quad_perm:[2,3,0,1] row_mask:0xf bank_mask:0xf bound_ctrl:1
	v_mov_b32_dpp v134, v132 quad_perm:[2,3,0,1] row_mask:0xf bank_mask:0xf bound_ctrl:1
	v_mov_b32_dpp v135, v133 quad_perm:[2,3,0,1] row_mask:0xf bank_mask:0xf bound_ctrl:1
	v_mov_b32_dpp v138, v136 quad_perm:[2,3,0,1] row_mask:0xf bank_mask:0xf bound_ctrl:1
	v_mov_b32_dpp v139, v137 quad_perm:[2,3,0,1] row_mask:0xf bank_mask:0xf bound_ctrl:1
	v_mov_b32_dpp v142, v140 quad_perm:[2,3,0,1] row_mask:0xf bank_mask:0xf bound_ctrl:1
	v_mov_b32_dpp v143, v141 quad_perm:[2,3,0,1] row_mask:0xf bank_mask:0xf bound_ctrl:1
	v_mov_b32_dpp v146, v144 quad_perm:[2,3,0,1] row_mask:0xf bank_mask:0xf bound_ctrl:1
	v_mov_b32_dpp v147, v145 quad_perm:[2,3,0,1] row_mask:0xf bank_mask:0xf bound_ctrl:1
	v_mov_b32_dpp v150, v148 quad_perm:[2,3,0,1] row_mask:0xf bank_mask:0xf bound_ctrl:1
	v_mov_b32_dpp v151, v149 quad_perm:[2,3,0,1] row_mask:0xf bank_mask:0xf bound_ctrl:1
	v_mov_b32_dpp v154, v152 quad_perm:[2,3,0,1] row_mask:0xf bank_mask:0xf bound_ctrl:1
	v_mov_b32_dpp v155, v153 quad_perm:[2,3,0,1] row_mask:0xf bank_mask:0xf bound_ctrl:1
	v_mov_b32_dpp v158, v156 quad_perm:[2,3,0,1] row_mask:0xf bank_mask:0xf bound_ctrl:1
	v_mov_b32_dpp v159, v157 quad_perm:[2,3,0,1] row_mask:0xf bank_mask:0xf bound_ctrl:1
	v_mov_b32_dpp v178, v168 quad_perm:[2,3,0,1] row_mask:0xf bank_mask:0xf bound_ctrl:1
	v_mov_b32_dpp v179, v169 quad_perm:[2,3,0,1] row_mask:0xf bank_mask:0xf bound_ctrl:1
	v_mov_b32_dpp v188, v182 quad_perm:[2,3,0,1] row_mask:0xf bank_mask:0xf bound_ctrl:1
	v_mov_b32_dpp v189, v183 quad_perm:[2,3,0,1] row_mask:0xf bank_mask:0xf bound_ctrl:1
	v_mov_b32_dpp v176, v164 quad_perm:[2,3,0,1] row_mask:0xf bank_mask:0xf bound_ctrl:1
	v_mov_b32_dpp v177, v165 quad_perm:[2,3,0,1] row_mask:0xf bank_mask:0xf bound_ctrl:1
	v_mov_b32_dpp v184, v180 quad_perm:[2,3,0,1] row_mask:0xf bank_mask:0xf bound_ctrl:1
	v_mov_b32_dpp v185, v181 quad_perm:[2,3,0,1] row_mask:0xf bank_mask:0xf bound_ctrl:1
	v_mov_b32_dpp v172, v162 quad_perm:[2,3,0,1] row_mask:0xf bank_mask:0xf bound_ctrl:1
	v_mov_b32_dpp v173, v163 quad_perm:[2,3,0,1] row_mask:0xf bank_mask:0xf bound_ctrl:1
	v_mov_b32_dpp v186, v174 quad_perm:[2,3,0,1] row_mask:0xf bank_mask:0xf bound_ctrl:1
	v_mov_b32_dpp v187, v175 quad_perm:[2,3,0,1] row_mask:0xf bank_mask:0xf bound_ctrl:1
	v_mov_b32_dpp v166, v160 quad_perm:[2,3,0,1] row_mask:0xf bank_mask:0xf bound_ctrl:1
	v_mov_b32_dpp v167, v161 quad_perm:[2,3,0,1] row_mask:0xf bank_mask:0xf bound_ctrl:1
	v_pk_add_f32 v[122:123], v[122:123], v[126:127]
	v_pk_add_f32 v[128:129], v[128:129], v[130:131]
	v_pk_add_f32 v[132:133], v[132:133], v[134:135]
	v_pk_add_f32 v[136:137], v[136:137], v[138:139]
	v_pk_add_f32 v[140:141], v[140:141], v[142:143]
	v_pk_add_f32 v[144:145], v[144:145], v[146:147]
	v_pk_add_f32 v[148:149], v[148:149], v[150:151]
	v_pk_add_f32 v[152:153], v[152:153], v[154:155]
	v_pk_add_f32 v[156:157], v[156:157], v[158:159]
	v_pk_add_f32 v[168:169], v[168:169], v[178:179]
	v_pk_add_f32 v[182:183], v[182:183], v[188:189]
	v_pk_add_f32 v[164:165], v[164:165], v[176:177]
	v_pk_add_f32 v[180:181], v[180:181], v[184:185]
	v_pk_add_f32 v[162:163], v[162:163], v[172:173]
	v_pk_add_f32 v[174:175], v[174:175], v[186:187]
; template <int CTRL> DI float dpp_f(float v) { return __builtin_bit_cast(float, __builtin_amdgcn_update_dpp(0, __builtin_bit_cast(int, v), CTRL, 0xF, 0xF, true)); }
; DI float row16_sum(float v) {
;     v += dpp_f<0xB1>(v);
;     v += dpp_f<0x4E>(v);
;     v += dpp_f<0x141>(v);
;     v += dpp_f<0x140>(v);
;     return v;
; }
; DI void unit_A(const Params& p, char* lds, int l, int chunk, int h) {
;     ...
;             for (int i = 0; i < 4; ++i) { sv[mt][i] = row16_sum(sv[mt][i]); ssv[mt][i] = row16_sum(ssv[mt][i]); }
;         if (l15 == 0) {
; #pragma unroll
;             for (int mt = 0; mt < 4; ++mt)
; #pragma unroll
;                 for (int i = 0; i < 4; ++i) { const int row = wr * 64 + mt * 16 + quad * 4 + i; *(f32x2*)&stat[(row * 4 + wc) * 2] = (f32x2){sv[mt][i], ssv[mt][i]}; }
;         }
	v_pk_add_f32 v[160:161], v[160:161], v[166:167]
	v_lshlrev_b32_e32 v101, 2, v190
	v_mov_b32_dpp v126, v122 row_half_mirror row_mask:0xf bank_mask:0xf bound_ctrl:1
	v_mov_b32_dpp v127, v123 row_half_mirror row_mask:0xf bank_mask:0xf bound_ctrl:1
	v_mov_b32_dpp v130, v128 row_half_mirror row_mask:0xf bank_mask:0xf bound_ctrl:1
	v_mov_b32_dpp v131, v129 row_half_mirror row_mask:0xf bank_mask:0xf bound_ctrl:1
	v_mov_b32_dpp v134, v132 row_half_mirror row_mask:0xf bank_mask:0xf bound_ctrl:1
	v_mov_b32_dpp v135, v133 row_half_mirror row_mask:0xf bank_mask:0xf bound_ctrl:1
	v_mov_b32_dpp v138, v136 row_half_mirror row_mask:0xf bank_mask:0xf bound_ctrl:1
	v_mov_b32_dpp v139, v137 row_half_mirror row_mask:0xf bank_mask:0xf bound_ctrl:1
	v_mov_b32_dpp v142, v140 row_half_mirror row_mask:0xf bank_mask:0xf bound_ctrl:1
	v_mov_b32_dpp v143, v141 row_half_mirror row_mask:0xf bank_mask:0xf bound_ctrl:1
	v_mov_b32_dpp v146, v144 row_half_mirror row_mask:0xf bank_mask:0xf bound_ctrl:1
	v_mov_b32_dpp v147, v145 row_half_mirror row_mask:0xf bank_mask:0xf bound_ctrl:1
	v_mov_b32_dpp v150, v148 row_half_mirror row_mask:0xf bank_mask:0xf bound_ctrl:1
	v_mov_b32_dpp v151, v149 row_half_mirror row_mask:0xf bank_mask:0xf bound_ctrl:1
	v_mov_b32_dpp v154, v152 row_half_mirror row_mask:0xf bank_mask:0xf bound_ctrl:1
	v_mov_b32_dpp v155, v153 row_half_mirror row_mask:0xf bank_mask:0xf bound_ctrl:1
	v_mov_b32_dpp v158, v156 row_half_mirror row_mask:0xf bank_mask:0xf bound_ctrl:1
	v_mov_b32_dpp v159, v157 row_half_mirror row_mask:0xf bank_mask:0xf bound_ctrl:1
	v_mov_b32_dpp v178, v168 row_half_mirror row_mask:0xf bank_mask:0xf bound_ctrl:1
	v_mov_b32_dpp v179, v169 row_half_mirror row_mask:0xf bank_mask:0xf bound_ctrl:1
	v_mov_b32_dpp v188, v182 row_half_mirror row_mask:0xf bank_mask:0xf bound_ctrl:1
	v_mov_b32_dpp v189, v183 row_half_mirror row_mask:0xf bank_mask:0xf bound_ctrl:1
	v_mov_b32_dpp v176, v164 row_half_mirror row_mask:0xf bank_mask:0xf bound_ctrl:1
	v_mov_b32_dpp v177, v165 row_half_mirror row_mask:0xf bank_mask:0xf bound_ctrl:1
	v_mov_b32_dpp v184, v180 row_half_mirror row_mask:0xf bank_mask:0xf bound_ctrl:1
	v_mov_b32_dpp v185, v181 row_half_mirror row_mask:0xf bank_mask:0xf bound_ctrl:1
	v_mov_b32_dpp v172, v162 row_half_mirror row_mask:0xf bank_mask:0xf bound_ctrl:1
	v_mov_b32_dpp v173, v163 row_half_mirror row_mask:0xf bank_mask:0xf bound_ctrl:1
	v_mov_b32_dpp v186, v174 row_half_mirror row_mask:0xf bank_mask:0xf bound_ctrl:1
	v_mov_b32_dpp v187, v175 row_half_mirror row_mask:0xf bank_mask:0xf bound_ctrl:1
	v_mov_b32_dpp v166, v160 row_half_mirror row_mask:0xf bank_mask:0xf bound_ctrl:1
	v_mov_b32_dpp v167, v161 row_half_mirror row_mask:0xf bank_mask:0xf bound_ctrl:1
	v_pk_add_f32 v[122:123], v[122:123], v[126:127]
	v_pk_add_f32 v[128:129], v[128:129], v[130:131]
	v_pk_add_f32 v[132:133], v[132:133], v[134:135]
	v_pk_add_f32 v[136:137], v[136:137], v[138:139]
	v_pk_add_f32 v[140:141], v[140:141], v[142:143]
	v_pk_add_f32 v[144:145], v[144:145], v[146:147]
	v_pk_add_f32 v[148:149], v[148:149], v[150:151]
	v_pk_add_f32 v[152:153], v[152:153], v[154:155]
	v_pk_add_f32 v[156:157], v[156:157], v[158:159]
	v_pk_add_f32 v[168:169], v[168:169], v[178:179]
	v_pk_add_f32 v[182:183], v[182:183], v[188:189]
	v_pk_add_f32 v[164:165], v[164:165], v[176:177]
	v_pk_add_f32 v[180:181], v[180:181], v[184:185]
	v_pk_add_f32 v[162:163], v[162:163], v[172:173]
	v_pk_add_f32 v[174:175], v[174:175], v[186:187]
	v_pk_add_f32 v[160:161], v[160:161], v[166:167]
	v_or_b32_e32 v204, v101, v124
	v_mov_b32_dpp v126, v122 row_mirror row_mask:0xf bank_mask:0xf bound_ctrl:1
	v_mov_b32_dpp v127, v123 row_mirror row_mask:0xf bank_mask:0xf bound_ctrl:1
	v_mov_b32_dpp v130, v128 row_mirror row_mask:0xf bank_mask:0xf bound_ctrl:1
	v_mov_b32_dpp v131, v129 row_mirror row_mask:0xf bank_mask:0xf bound_ctrl:1
	v_mov_b32_dpp v134, v132 row_mirror row_mask:0xf bank_mask:0xf bound_ctrl:1
	v_mov_b32_dpp v135, v133 row_mirror row_mask:0xf bank_mask:0xf bound_ctrl:1
	v_mov_b32_dpp v138, v136 row_mirror row_mask:0xf bank_mask:0xf bound_ctrl:1
	v_mov_b32_dpp v139, v137 row_mirror row_mask:0xf bank_mask:0xf bound_ctrl:1
	v_mov_b32_dpp v142, v140 row_mirror row_mask:0xf bank_mask:0xf bound_ctrl:1
	v_mov_b32_dpp v143, v141 row_mirror row_mask:0xf bank_mask:0xf bound_ctrl:1
	v_mov_b32_dpp v146, v144 row_mirror row_mask:0xf bank_mask:0xf bound_ctrl:1
	v_mov_b32_dpp v147, v145 row_mirror row_mask:0xf bank_mask:0xf bound_ctrl:1
	v_mov_b32_dpp v150, v148 row_mirror row_mask:0xf bank_mask:0xf bound_ctrl:1
	v_mov_b32_dpp v151, v149 row_mirror row_mask:0xf bank_mask:0xf bound_ctrl:1
	v_mov_b32_dpp v154, v152 row_mirror row_mask:0xf bank_mask:0xf bound_ctrl:1
	v_mov_b32_dpp v155, v153 row_mirror row_mask:0xf bank_mask:0xf bound_ctrl:1
	v_mov_b32_dpp v158, v156 row_mirror row_mask:0xf bank_mask:0xf bound_ctrl:1
	v_mov_b32_dpp v159, v157 row_mirror row_mask:0xf bank_mask:0xf bound_ctrl:1
	v_mov_b32_dpp v178, v168 row_mirror row_mask:0xf bank_mask:0xf bound_ctrl:1
	v_mov_b32_dpp v179, v169 row_mirror row_mask:0xf bank_mask:0xf bound_ctrl:1
	v_mov_b32_dpp v188, v182 row_mirror row_mask:0xf bank_mask:0xf bound_ctrl:1
	v_mov_b32_dpp v189, v183 row_mirror row_mask:0xf bank_mask:0xf bound_ctrl:1
	v_mov_b32_dpp v176, v164 row_mirror row_mask:0xf bank_mask:0xf bound_ctrl:1
	v_mov_b32_dpp v177, v165 row_mirror row_mask:0xf bank_mask:0xf bound_ctrl:1
	v_mov_b32_dpp v184, v180 row_mirror row_mask:0xf bank_mask:0xf bound_ctrl:1
	v_mov_b32_dpp v185, v181 row_mirror row_mask:0xf bank_mask:0xf bound_ctrl:1
	v_mov_b32_dpp v172, v162 row_mirror row_mask:0xf bank_mask:0xf bound_ctrl:1
	v_mov_b32_dpp v173, v163 row_mirror row_mask:0xf bank_mask:0xf bound_ctrl:1
	v_mov_b32_dpp v186, v174 row_mirror row_mask:0xf bank_mask:0xf bound_ctrl:1
	v_mov_b32_dpp v187, v175 row_mirror row_mask:0xf bank_mask:0xf bound_ctrl:1
	v_mov_b32_dpp v166, v160 row_mirror row_mask:0xf bank_mask:0xf bound_ctrl:1
	v_mov_b32_dpp v167, v161 row_mirror row_mask:0xf bank_mask:0xf bound_ctrl:1
	v_cmp_ne_u32_e32 vcc, 0, v194
	v_lshlrev_b32_e32 v200, 5, v204
	s_and_saveexec_b64 s[6:7], vcc
	s_xor_b64 s[6:7], exec, s[6:7]
	s_cbranch_execz .LBB0_830
	v_lshlrev_b32_e32 v200, 5, v204
	v_or_b32_e32 v202, 32, v200
	v_or_b32_e32 v203, 64, v200
	v_or_b32_e32 v201, 0x60, v200
	v_or_b32_e32 v198, 0x200, v200
	v_or_b32_e32 v197, 0x220, v200
	v_or_b32_e32 v199, 0x240, v200
	v_or_b32_e32 v196, 0x260, v200
	v_or_b32_e32 v171, 0x400, v200
	v_or_b32_e32 v170, 0x420, v200
	v_or_b32_e32 v195, 0x440, v200
	v_or_b32_e32 v125, 0x460, v200
	v_or_b32_e32 v103, 0x600, v200
	v_or_b32_e32 v101, 0x620, v200
	v_or_b32_e32 v105, 0x640, v200
	v_or_b32_e32 v0, 0x660, v200

; DI int opaque_tid() { int t = threadIdx.x; asm volatile("" : "+v"(t)); return t; }
;     constexpr int WM = BM / WR, WN = BN / WC, MT = WM / 16, NT = WN / 16, ROWS = BM + BN, NCH = ROWS * 4, NIT = (NCH + 511) / 512, BUF = ROWS * 64, KT = 32;
;     constexpr int NTS = NT / NSEG, D = NST - 1;
;     static_assert(D == 1 || (NCH % 512 == 0), "deep ring needs a uniform per-thread load count");
;     const int tid = opaque_tid(), lane = tid & 63, wid = tid >> 6, wr = wid / WC, wc = wid % WC, l15 = lane & 15, quad = lane >> 4;
;     const int lrow = tid >> 2, lc = tid & 3;
;     const int lcg = lc ^ ((0 - (tid >> 4)) & 3);
;     const int rsw = (quad ^ ((0 - (l15 >> 2)) & 3)) << 4;
; #pragma unroll
;     for (int mt = 0; mt < MT; ++mt)
; #pragma unroll
;         for (int nt = 0; nt < NT; ++nt) acc[mt][nt] = (f32x4){0.f, 0.f, 0.f, 0.f};
;     const unsigned loff = (unsigned)(lrow * 64 + lcg * 16);
;     const int koff = (int)((blockIdx.x >> 3) + (blockIdx.x & 7) * 4) & (KT - 1);
;     auto issue_one = [&](int kt, int b, int i) {
;         const int row = lrow + 128 * i;
;         if ((NCH % 512 == 0) || (i < NCH / 512) || row < ROWS) {
;             const int kq = (kt + koff) & (KT - 1);
;             const char* ua = (const char*)A + (size_t)((DBG & 1) ? 0 : kq) * (BM * 64);
;             const char* ub = (const char*)Bt + (size_t)((DBG & 2) ? 0 : kq) * ((size_t)ldbk * 2);
;             const char* src;
;             if (BM % 128 == 0) src = (i < BM / 128) ? (ua + i * 8192 + loff) : (ub + (i * 128 - BM) * 64 + loff);
;             else if (i == 0) src = (lrow < BM) ? (ua + loff) : (ub + loff - BM * 64);
;             else src = ub + (i * 128 - BM) * 64 + loff;
;             __builtin_amdgcn_global_load_lds((const unsigned*)src, (unsigned*)(lds + b * BUF + i * 8192 + tid * 16), 16, 0, 0);
;         }
;     };
;     auto issue = [&](int kt, int b) {
; #pragma unroll
;         for (int i = 0; i < NIT; ++i) issue_one(kt, b, i);
;     ...
;     __syncthreads();
; #pragma unroll
;     for (int d = 0; d < D; ++d) issue(d, d);
; DI void unit_B1(const Params& p, char* lds, int l, int chunk) {
;     ...
;     gemm_main<128, 512, 2, 4, 1, true, 3>(xb + (size_t)chunk * 128 * 1024, WS_PTR(const bf16_t, OFF_WIN) + (size_t)l * 2560 * 1024 + (size_t)1536 * 32, 2560 * 32, lds, acc);
.LBB0_892:
	s_andn2_b64 vcc, exec, s[6:7]
	s_cbranch_vccnz .LBB0_662
	v_mov_b32_e32 v135, v212
	v_mov_b32_e32 v4, v212
	s_ashr_i32 s3, s2, 31
	v_ashrrev_i32_e32 v5, 6, v4
	v_lshrrev_b32_e32 v0, 30, v5
	v_add_u32_e32 v0, v5, v0
	v_ashrrev_i32_e32 v6, 2, v0
	v_lshrrev_b32_e32 v0, 4, v4
	v_sub_u32_e32 v0, 0, v0
	v_lshlrev_b32_e32 v2, 2, v4
	s_lshl_b64 s[0:1], s[2:3], 18
	v_readlane_b32 s6, v243, 56
	v_and_b32_e32 v2, 48, v2
	v_xor_b32_e32 v0, v4, v0
	v_lshlrev_b32_e32 v8, 4, v4
	s_add_u32 s8, s6, s0
	v_readlane_b32 s0, v243, 40
	v_sub_u32_e32 v7, 0, v2
	v_and_b32_e32 v2, 0xffffffc0, v8
	v_lshlrev_b32_e32 v0, 4, v0
	s_addc_u32 s9, s0, s1
	v_and_or_b32 v0, v0, 48, v2
	v_lshl_add_u64 v[130:131], s[8:9], 0, v[0:1]
	v_readlane_b32 s8, v243, 25
	v_add_u32_e32 v134, 0, v8
	v_readlane_b32 s9, v243, 26
	v_readfirstlane_b32 s7, v134
	s_mov_b32 m0, s7
	v_lshl_add_u64 v[2:3], v[130:131], 0, s[8:9]
	s_waitcnt lgkmcnt(0)
	s_barrier
	global_load_lds_dwordx4 v[2:3], off
	v_add_u32_e32 v2, 0x2000, v134
	v_readlane_b32 s8, v243, 42
	v_readfirstlane_b32 s7, v2
	s_mov_b32 m0, s7
	v_readlane_b32 s9, v243, 43
	v_add_u32_e32 v2, 0x4000, v134
	v_add_u32_e32 v9, 0xa000, v134
	v_readfirstlane_b32 s7, v2
	v_add_u32_e32 v2, 0x6000, v134
	s_mov_b32 s1, 2
	global_load_lds_dwordx4 v0, s[8:9]
	v_readlane_b32 s8, v243, 44
	s_mov_b32 m0, s7
	v_readlane_b32 s9, v243, 45
	v_readfirstlane_b32 s7, v2
	v_add_u32_e32 v2, 0x8000, v134
	s_mov_b32 s0, 4
	s_mov_b32 s6, 0
	v_lshl_add_u64 v[132:133], s[48:49], 0, v[0:1]
	global_load_lds_dwordx4 v0, s[8:9]
	v_readlane_b32 s8, v243, 46
	s_mov_b32 m0, s7
	v_readlane_b32 s9, v243, 47
	v_readfirstlane_b32 s7, v2
	s_nop 3
	global_load_lds_dwordx4 v0, s[8:9]
	v_readlane_b32 s8, v243, 48
	s_mov_b32 m0, s7
	v_readlane_b32 s9, v243, 49
	v_readfirstlane_b32 s7, v9
	s_nop 3
	global_load_lds_dwordx4 v0, s[8:9]
	v_readlane_b32 s8, v243, 5
	v_readlane_b32 s9, v243, 6
	s_mov_b32 m0, s7
	s_nop 0
	v_lshl_add_u64 v[2:3], v[130:131], 0, s[8:9]
	global_load_lds_dwordx4 v[2:3], off
	v_add_u32_e32 v2, 0xc000, v134
	v_readlane_b32 s8, v243, 50
	v_readfirstlane_b32 s7, v2
	v_add_u32_e32 v2, 0xe000, v134
	s_mov_b32 m0, s7
	v_readlane_b32 s9, v243, 51
	v_readfirstlane_b32 s7, v2
	v_bitop3_b32 v3, v4, 48, v7 bitop3:0x48
	v_add_u32_e32 v136, 0, v3
	v_lshlrev_b32_e32 v3, 6, v4
	v_and_b32_e32 v3, 0x3c0, v3
	global_load_lds_dwordx4 v0, s[8:9]
	s_mov_b32 m0, s7
	s_add_i32 s7, 0, 0x10000
	v_readlane_b32 s8, v243, 52
	v_add_u32_e32 v2, s7, v8
	v_readlane_b32 s9, v243, 53
	v_readfirstlane_b32 s7, v2
	v_lshl_or_b32 v137, v6, 12, v3
	s_nop 2
	global_load_lds_dwordx4 v0, s[8:9]
	s_mov_b32 m0, s7
	v_readlane_b32 s8, v243, 58
	v_readlane_b32 s7, v243, 31
	v_readlane_b32 s9, v243, 59
	s_nop 0
	v_add_u32_e32 v2, s7, v8
	s_nop 0
	v_readfirstlane_b32 s7, v2
	v_mul_i32_i24_e32 v2, 4, v6
	global_load_lds_dwordx4 v0, s[8:9]
	v_readlane_b32 s8, v243, 54
	s_mov_b32 m0, s7
	v_readlane_b32 s9, v243, 55
	v_sub_u32_e32 v2, v5, v2
	v_lshl_or_b32 v138, v2, 13, v3
	v_mov_b32_e32 v2, 0
	v_readlane_b32 s7, v243, 24
	v_mov_b32_e32 v3, v2
	global_load_lds_dwordx4 v0, s[8:9]
	v_mov_b32_e32 v4, v2
	v_mov_b32_e32 v5, v2
	v_mov_b32_e32 v6, v2
	v_mov_b32_e32 v7, v2
	v_mov_b32_e32 v8, v2
	v_mov_b32_e32 v9, v2
	v_mov_b32_e32 v10, v2
	v_mov_b32_e32 v11, v2
	v_mov_b32_e32 v12, v2
	v_mov_b32_e32 v13, v2
	v_mov_b32_e32 v14, v2
	v_mov_b32_e32 v15, v2
	v_mov_b32_e32 v16, v2
	v_mov_b32_e32 v17, v2
	v_mov_b32_e32 v18, v2
	v_mov_b32_e32 v19, v2
	v_mov_b32_e32 v20, v2
	v_mov_b32_e32 v21, v2
	v_mov_b32_e32 v22, v2
	v_mov_b32_e32 v23, v2
	v_mov_b32_e32 v24, v2
	v_mov_b32_e32 v25, v2
	v_mov_b32_e32 v26, v2
	v_mov_b32_e32 v27, v2
	v_mov_b32_e32 v28, v2
	v_mov_b32_e32 v29, v2
	v_mov_b32_e32 v30, v2
	v_mov_b32_e32 v31, v2
	v_mov_b32_e32 v32, v2
	v_mov_b32_e32 v33, v2
	v_mov_b32_e32 v34, v2
	v_mov_b32_e32 v35, v2
	v_mov_b32_e32 v36, v2
	v_mov_b32_e32 v37, v2
	v_mov_b32_e32 v38, v2
	v_mov_b32_e32 v39, v2
	v_mov_b32_e32 v40, v2
	v_mov_b32_e32 v41, v2
	v_mov_b32_e32 v42, v2
	v_mov_b32_e32 v43, v2
	v_mov_b32_e32 v44, v2
	v_mov_b32_e32 v45, v2
	v_mov_b32_e32 v46, v2
	v_mov_b32_e32 v47, v2
	v_mov_b32_e32 v48, v2
	v_mov_b32_e32 v49, v2
	v_mov_b32_e32 v50, v2
	v_mov_b32_e32 v51, v2
	v_mov_b32_e32 v52, v2
	v_mov_b32_e32 v53, v2
	v_mov_b32_e32 v54, v2
	v_mov_b32_e32 v55, v2
	v_mov_b32_e32 v56, v2
	v_mov_b32_e32 v57, v2
	v_mov_b32_e32 v58, v2
	v_mov_b32_e32 v59, v2
	v_mov_b32_e32 v60, v2
	v_mov_b32_e32 v61, v2
	v_mov_b32_e32 v62, v2
	v_mov_b32_e32 v63, v2
	v_mov_b32_e32 v64, v2
	v_mov_b32_e32 v65, v2
	v_mov_b32_e32 v66, v2
	v_mov_b32_e32 v67, v2
	v_mov_b32_e32 v68, v2
	v_mov_b32_e32 v69, v2
	v_mov_b32_e32 v70, v2
	v_mov_b32_e32 v71, v2
	v_mov_b32_e32 v72, v2
	v_mov_b32_e32 v73, v2
	v_mov_b32_e32 v74, v2
	v_mov_b32_e32 v75, v2
	v_mov_b32_e32 v76, v2
	v_mov_b32_e32 v77, v2
	v_mov_b32_e32 v78, v2
	v_mov_b32_e32 v79, v2
	v_mov_b32_e32 v80, v2
	v_mov_b32_e32 v81, v2
	v_mov_b32_e32 v82, v2
	v_mov_b32_e32 v83, v2
	v_mov_b32_e32 v84, v2
	v_mov_b32_e32 v85, v2
	v_mov_b32_e32 v86, v2
	v_mov_b32_e32 v87, v2
	v_mov_b32_e32 v88, v2
	v_mov_b32_e32 v89, v2
	v_mov_b32_e32 v90, v2
	v_mov_b32_e32 v91, v2
	v_mov_b32_e32 v92, v2
	v_mov_b32_e32 v93, v2
	v_mov_b32_e32 v94, v2
	v_mov_b32_e32 v95, v2
	v_mov_b32_e32 v96, v2
	v_mov_b32_e32 v97, v2
	v_mov_b32_e32 v98, v2
	v_mov_b32_e32 v99, v2
	v_mov_b32_e32 v100, v2
	v_mov_b32_e32 v101, v2
	v_mov_b32_e32 v102, v2
	v_mov_b32_e32 v103, v2
	v_mov_b32_e32 v104, v2
	v_mov_b32_e32 v105, v2
	v_mov_b32_e32 v106, v2
	v_mov_b32_e32 v107, v2
	v_mov_b32_e32 v108, v2
	v_mov_b32_e32 v109, v2
	v_mov_b32_e32 v110, v2
	v_mov_b32_e32 v111, v2
	v_mov_b32_e32 v112, v2
	v_mov_b32_e32 v113, v2
	v_mov_b32_e32 v114, v2
	v_mov_b32_e32 v115, v2
	v_mov_b32_e32 v116, v2
	v_mov_b32_e32 v117, v2
	v_mov_b32_e32 v118, v2
	v_mov_b32_e32 v119, v2
	v_mov_b32_e32 v120, v2
	v_mov_b32_e32 v121, v2
	v_mov_b32_e32 v122, v2
	v_mov_b32_e32 v123, v2
	v_mov_b32_e32 v124, v2
	v_mov_b32_e32 v125, v2
	v_mov_b32_e32 v126, v2
	v_mov_b32_e32 v127, v2
	v_mov_b32_e32 v128, v2
	v_mov_b32_e32 v129, v2
	v_readfirstlane_b32 s40, v212
	s_nop 3
	s_cmp_lt_u32 s40, 0x100
	s_cbranch_scc0 .Lpb1_c_entry
; template <int N> DI void wait_vm() { asm volatile("s_waitcnt vmcnt(%0)" ::"n"(N) : "memory"); }
; DI void raw_barrier() { asm volatile("" ::: "memory"); __builtin_amdgcn_s_barrier(); asm volatile("" ::: "memory"); }
;     ...
;     auto issue_one = [&](int kt, int b, int i) {
;         const int row = lrow + 128 * i;
;         if ((NCH % 512 == 0) || (i < NCH / 512) || row < ROWS) {
;             const int kq = (kt + koff) & (KT - 1);
;             const char* ua = (const char*)A + (size_t)((DBG & 1) ? 0 : kq) * (BM * 64);
;             const char* ub = (const char*)Bt + (size_t)((DBG & 2) ? 0 : kq) * ((size_t)ldbk * 2);
;             const char* src;
;             if (BM % 128 == 0) src = (i < BM / 128) ? (ua + i * 8192 + loff) : (ub + (i * 128 - BM) * 64 + loff);
;             else if (i == 0) src = (lrow < BM) ? (ua + loff) : (ub + loff - BM * 64);
;             else src = ub + (i * 128 - BM) * 64 + loff;
;             __builtin_amdgcn_global_load_lds((const unsigned*)src, (unsigned*)(lds + b * BUF + i * 8192 + tid * 16), 16, 0, 0);
;         }
;     };
;     auto issue = [&](int kt, int b) {
; #pragma unroll
;         for (int i = 0; i < NIT; ++i) issue_one(kt, b, i);
;     };
;     auto compute = [&](int cb, bool do_issue, int ikt, int ib) {
;         const char* base = lds + cb * BUF;
;         bf16x8 af[MT], bfr[NT];
; #pragma unroll
;         for (int nt = 0; nt < NT; ++nt) {
;             const int br = BM + (nt / NTS) * (BN / NSEG) + wc * (NTS * 16) + (nt % NTS) * 16;
;             bfr[nt] = *(const bf16x8*)(base + (br + l15) * 64 + rsw);
;         }
; #pragma unroll
;         for (int mt = 0; mt < MT; ++mt) af[mt] = *(const bf16x8*)(base + (wr * WM + mt * 16 + l15) * 64 + rsw);
;     ...
;     for (int d = 0; d < D; ++d) issue(d, d);
;     int cb = 0, ib = D;
;     for (int kt = 0; kt < KT; ++kt) {
;         if (D > 1 && kt + D - 1 < KT) wait_vm<(D - 1) * NIT>(); else wait_vm<0>();
;         raw_barrier();
	s_setprio 1
	s_lshl_b32 s7, s40, 5
	s_lshl_b32 s40, s40, 4
	v_add_u32_e32 v227, s40, v0
	v_readfirstlane_b32 s8, v130
	v_readfirstlane_b32 s9, v131
	v_readfirstlane_b32 s40, v0
	s_nop 3
	s_sub_u32 vcc_lo, s8, s40
	s_subb_u32 vcc_hi, s9, 0
	s_mul_i32 s8, s1, 0xa000
	s_add_u32 s8, s8, s7
	s_mov_b32 m0, s8
	s_add_i32 s40, s59, s0
	s_and_b32 s40, s40, 62
	s_lshl_b32 s8, s40, 12
	s_add_u32 s8, vcc_lo, s8
	s_addc_u32 s9, vcc_hi, 0
	s_mul_i32 s40, s40, 0x14000
	global_load_lds_dwordx4 v227, s[8:9]
	global_load_lds_dwordx4 v227, s[8:9] offset:1024
	s_add_u32 s8, s48, s40
	s_addc_u32 s9, s49, 0
	s_add_u32 m0, m0, 0x2000
	s_nop 0
	global_load_lds_dwordx4 v227, s[8:9]
	global_load_lds_dwordx4 v227, s[8:9] offset:1024
	s_add_u32 s8, s8, 0x2000
	s_addc_u32 s9, s9, 0
	s_add_u32 m0, m0, 0x2000
	s_nop 0
	global_load_lds_dwordx4 v227, s[8:9]
	global_load_lds_dwordx4 v227, s[8:9] offset:1024
	s_add_u32 s8, s8, 0x2000
	s_addc_u32 s9, s9, 0
	s_add_u32 m0, m0, 0x2000
	s_nop 0
	global_load_lds_dwordx4 v227, s[8:9]
	global_load_lds_dwordx4 v227, s[8:9] offset:1024
	s_add_u32 s8, s8, 0x2000
	s_addc_u32 s9, s9, 0
	s_add_u32 m0, m0, 0x2000
	s_nop 0
	global_load_lds_dwordx4 v227, s[8:9]
	global_load_lds_dwordx4 v227, s[8:9] offset:1024
	s_add_i32 s0, s0, 2
	s_mov_b32 s1, 0
	s_mov_b32 s6, 1
	s_waitcnt vmcnt(15)
	s_barrier
	v_add_u32_e32 v225, v136, v138
	v_add_u32_e32 v224, v136, v137
	ds_read_b128 v[144:147], v224
	ds_read_b128 v[152:155], v224 offset:1024
	ds_read_b128 v[180:183], v224 offset:2048
	ds_read_b128 v[140:143], v225 offset:8192
	ds_read_b128 v[148:151], v225 offset:9216
	ds_read_b128 v[156:159], v225 offset:10240
	ds_read_b128 v[160:163], v225 offset:11264
	ds_read_b128 v[164:167], v225 offset:12288
	ds_read_b128 v[168:171], v225 offset:13312
	ds_read_b128 v[172:175], v225 offset:14336
	ds_read_b128 v[176:179], v225 offset:15360
	ds_read_b128 v[184:187], v224 offset:3072

; DI unsigned pk2(float lo, float hi) { const f32x2 v = {lo, hi}; const bf16x2_t b = __builtin_convertvector(v, bf16x2_t); return __builtin_bit_cast(unsigned, b); }
; DI float silu_f(float x) { return x * sigmoid_f(x); }
;     ...
;     auto compute = [&](int cb, bool do_issue, int ikt, int ib) {
;         const char* base = lds + cb * BUF;
;         bf16x8 af[MT], bfr[NT];
; #pragma unroll
;         for (int nt = 0; nt < NT; ++nt) {
;             const int br = BM + (nt / NTS) * (BN / NSEG) + wc * (NTS * 16) + (nt % NTS) * 16;
;             bfr[nt] = *(const bf16x8*)(base + (br + l15) * 64 + rsw);
;         }
; #pragma unroll
;         for (int mt = 0; mt < MT; ++mt) af[mt] = *(const bf16x8*)(base + (wr * WM + mt * 16 + l15) * 64 + rsw);
;         constexpr int TOT = MT * NT, PER = (TOT + NIT - 1) / NIT;
; #pragma unroll
;         for (int part = 0; part < NIT; ++part) {
; #pragma unroll
;             for (int q = 0; q < PER; ++q) {
;                 const int idx = part * PER + q;
;                 if (idx < TOT) {
;                     const int mt = idx / NT, nt = idx % NT;
;                     acc[mt][nt] = SWAP ? mfma16(bfr[nt], af[mt], acc[mt][nt]) : mfma16(af[mt], bfr[nt], acc[mt][nt]);
;     ...
;     for (int kt = 0; kt < KT; ++kt) {
;         if (D > 1 && kt + D - 1 < KT) wait_vm<(D - 1) * NIT>(); else wait_vm<0>();
;         raw_barrier();
;         compute(cb, kt + D < KT, kt + D, ib);
; DI void unit_B1(const Params& p, char* lds, int l, int chunk) {
;     ...
;     bf16_t* sgd = WS_PTR(bf16_t, OFF_SG) + (size_t)chunk * 128 * 256;
;     bf16_t* xbd = WS_PTR(bf16_t, OFF_XBB) + (size_t)(chunk >> 4) * 16 * 2048 * 16;
; #pragma unroll
;     for (int mt = 0; mt < 4; ++mt) {
;         const int tok = wr * 64 + mt * 16 + l15;
; #pragma unroll
;         for (int nt = 0; nt < 8; ++nt) {
;             f32x4 v = acc[mt][nt];
;             if (wc >= 2) {
;                 v[0] = silu_f(v[0]); v[1] = silu_f(v[1]); v[2] = silu_f(v[2]); v[3] = silu_f(v[3]);
;                 const int col = (wc & 1) * 128 + nt * 16 + quad * 4;
;                 *(u32x2*)(sgd + (size_t)tok * 256 + col) = (u32x2){pk2(v[0], v[1]), pk2(v[2], v[3])};
;             } else {
;                 const int g = (wc & 1) * 8 + nt, tb = (chunk & 15) * 128 + tok;
;                 *(u32x2*)(xbd + ((size_t)g * 2048 + tb) * 16 + quad * 4) = (u32x2){pk2(v[0], v[1]), pk2(v[2], v[3])};
.Lpb1_join:
	s_setprio 0
	s_waitcnt vmcnt(5)
	s_barrier
	v_add_u32_e32 v0, v136, v138
	v_add_u32_e32 v134, v136, v137
	ds_read_b128 v[130:133], v0 offset:8192
	ds_read_b128 v[136:139], v134
	ds_read_b128 v[140:143], v0 offset:9216
	ds_read_b128 v[144:147], v134 offset:1024
	ds_read_b128 v[148:151], v0 offset:10240
	ds_read_b128 v[152:155], v0 offset:11264
	ds_read_b128 v[156:159], v0 offset:12288
	ds_read_b128 v[160:163], v0 offset:13312
	ds_read_b128 v[164:167], v0 offset:14336
	ds_read_b128 v[168:171], v0 offset:15360
	ds_read_b128 v[172:175], v134 offset:2048
	ds_read_b128 v[176:179], v134 offset:3072
	s_waitcnt lgkmcnt(0)
	v_mfma_f32_16x16x32_bf16 v[126:129], v[130:133], v[136:139], v[126:129]
	v_bfe_u32 v180, v135, 6, 2
	v_mfma_f32_16x16x32_bf16 v[122:125], v[140:143], v[136:139], v[122:125]
	v_mfma_f32_16x16x32_bf16 v[118:121], v[148:151], v[136:139], v[118:121]
	v_mfma_f32_16x16x32_bf16 v[114:117], v[152:155], v[136:139], v[114:117]
	v_mfma_f32_16x16x32_bf16 v[110:113], v[156:159], v[136:139], v[110:113]
	v_mfma_f32_16x16x32_bf16 v[106:109], v[160:163], v[136:139], v[106:109]
	v_mfma_f32_16x16x32_bf16 v[102:105], v[164:167], v[136:139], v[102:105]
	v_mfma_f32_16x16x32_bf16 v[98:101], v[168:171], v[136:139], v[98:101]
	v_mfma_f32_16x16x32_bf16 v[94:97], v[130:133], v[144:147], v[94:97]
	v_mfma_f32_16x16x32_bf16 v[90:93], v[140:143], v[144:147], v[90:93]
	v_mfma_f32_16x16x32_bf16 v[86:89], v[148:151], v[144:147], v[86:89]
	v_mfma_f32_16x16x32_bf16 v[82:85], v[152:155], v[144:147], v[82:85]
	v_mfma_f32_16x16x32_bf16 v[78:81], v[156:159], v[144:147], v[78:81]
	v_mfma_f32_16x16x32_bf16 v[74:77], v[160:163], v[144:147], v[74:77]
	v_mfma_f32_16x16x32_bf16 v[70:73], v[164:167], v[144:147], v[70:73]
	v_mfma_f32_16x16x32_bf16 v[66:69], v[168:171], v[144:147], v[66:69]
	v_mfma_f32_16x16x32_bf16 v[62:65], v[130:133], v[172:175], v[62:65]
	v_mfma_f32_16x16x32_bf16 v[58:61], v[140:143], v[172:175], v[58:61]
	v_mfma_f32_16x16x32_bf16 v[54:57], v[148:151], v[172:175], v[54:57]
	v_mfma_f32_16x16x32_bf16 v[50:53], v[152:155], v[172:175], v[50:53]
	v_mfma_f32_16x16x32_bf16 v[46:49], v[156:159], v[172:175], v[46:49]
	v_mfma_f32_16x16x32_bf16 v[42:45], v[160:163], v[172:175], v[42:45]
	v_mfma_f32_16x16x32_bf16 v[38:41], v[164:167], v[172:175], v[38:41]
	v_mfma_f32_16x16x32_bf16 v[34:37], v[168:171], v[172:175], v[34:37]
	v_mfma_f32_16x16x32_bf16 v[30:33], v[130:133], v[176:179], v[30:33]
	v_mfma_f32_16x16x32_bf16 v[26:29], v[140:143], v[176:179], v[26:29]
	v_mfma_f32_16x16x32_bf16 v[22:25], v[148:151], v[176:179], v[22:25]
	v_mfma_f32_16x16x32_bf16 v[18:21], v[152:155], v[176:179], v[18:21]
	v_mfma_f32_16x16x32_bf16 v[14:17], v[156:159], v[176:179], v[14:17]
	v_mfma_f32_16x16x32_bf16 v[10:13], v[160:163], v[176:179], v[10:13]
	v_mfma_f32_16x16x32_bf16 v[6:9], v[164:167], v[176:179], v[6:9]
	v_mfma_f32_16x16x32_bf16 v[2:5], v[168:171], v[176:179], v[2:5]
	s_waitcnt vmcnt(0)
	s_barrier
	ds_read_b128 v[130:133], v0 offset:49152
	ds_read_b128 v[136:139], v134 offset:40960
	ds_read_b128 v[140:143], v0 offset:50176
	ds_read_b128 v[144:147], v134 offset:41984
	ds_read_b128 v[148:151], v0 offset:51200
	ds_read_b128 v[152:155], v0 offset:52224
	ds_read_b128 v[156:159], v0 offset:53248
	ds_read_b128 v[160:163], v0 offset:54272
	ds_read_b128 v[164:167], v0 offset:55296
	ds_read_b128 v[168:171], v0 offset:56320
	ds_read_b128 v[172:175], v134 offset:43008
	ds_read_b128 v[176:179], v134 offset:44032
	s_waitcnt lgkmcnt(0)
	v_mfma_f32_16x16x32_bf16 v[126:129], v[130:133], v[136:139], v[126:129]
	v_and_b32_e32 v181, 15, v135
	v_mfma_f32_16x16x32_bf16 v[122:125], v[140:143], v[136:139], v[122:125]
	v_mfma_f32_16x16x32_bf16 v[118:121], v[148:151], v[136:139], v[118:121]
	v_mfma_f32_16x16x32_bf16 v[114:117], v[152:155], v[136:139], v[114:117]
	v_mfma_f32_16x16x32_bf16 v[110:113], v[156:159], v[136:139], v[110:113]
	v_mfma_f32_16x16x32_bf16 v[106:109], v[160:163], v[136:139], v[106:109]
	v_mfma_f32_16x16x32_bf16 v[102:105], v[164:167], v[136:139], v[102:105]
	v_mfma_f32_16x16x32_bf16 v[98:101], v[168:171], v[136:139], v[98:101]
	v_mfma_f32_16x16x32_bf16 v[94:97], v[130:133], v[144:147], v[94:97]
	v_mfma_f32_16x16x32_bf16 v[90:93], v[140:143], v[144:147], v[90:93]
	v_mfma_f32_16x16x32_bf16 v[86:89], v[148:151], v[144:147], v[86:89]
	v_mfma_f32_16x16x32_bf16 v[82:85], v[152:155], v[144:147], v[82:85]
	v_mfma_f32_16x16x32_bf16 v[78:81], v[156:159], v[144:147], v[78:81]
	v_mfma_f32_16x16x32_bf16 v[74:77], v[160:163], v[144:147], v[74:77]
	v_mfma_f32_16x16x32_bf16 v[70:73], v[164:167], v[144:147], v[70:73]
	v_mfma_f32_16x16x32_bf16 v[66:69], v[168:171], v[144:147], v[66:69]
	v_mfma_f32_16x16x32_bf16 v[62:65], v[130:133], v[172:175], v[62:65]
	v_mfma_f32_16x16x32_bf16 v[58:61], v[140:143], v[172:175], v[58:61]
	v_mfma_f32_16x16x32_bf16 v[54:57], v[148:151], v[172:175], v[54:57]
	v_mfma_f32_16x16x32_bf16 v[50:53], v[152:155], v[172:175], v[50:53]
	v_mfma_f32_16x16x32_bf16 v[46:49], v[156:159], v[172:175], v[46:49]
	v_mfma_f32_16x16x32_bf16 v[42:45], v[160:163], v[172:175], v[42:45]
	v_mfma_f32_16x16x32_bf16 v[38:41], v[164:167], v[172:175], v[38:41]
	v_mfma_f32_16x16x32_bf16 v[34:37], v[168:171], v[172:175], v[34:37]
	v_mfma_f32_16x16x32_bf16 v[30:33], v[130:133], v[176:179], v[30:33]
	v_mfma_f32_16x16x32_bf16 v[26:29], v[140:143], v[176:179], v[26:29]
	v_mfma_f32_16x16x32_bf16 v[22:25], v[148:151], v[176:179], v[22:25]
	v_mfma_f32_16x16x32_bf16 v[18:21], v[152:155], v[176:179], v[18:21]
	v_mfma_f32_16x16x32_bf16 v[14:17], v[156:159], v[176:179], v[14:17]
	v_mfma_f32_16x16x32_bf16 v[10:13], v[160:163], v[176:179], v[10:13]
	v_mfma_f32_16x16x32_bf16 v[6:9], v[164:167], v[176:179], v[6:9]
	v_mfma_f32_16x16x32_bf16 v[2:5], v[168:171], v[176:179], v[2:5]
	s_lshl_b64 s[0:1], s[2:3], 16
	v_readlane_b32 s3, v244, 48
	s_add_u32 s8, s3, s0
	v_readlane_b32 s0, v244, 49
	s_addc_u32 s9, s0, s1
	s_ashr_i32 s6, s2, 4
	s_ashr_i32 s7, s6, 31
	s_lshl_b64 s[0:1], s[6:7], 20
	v_readlane_b32 s3, v243, 0
	s_add_u32 s10, s3, s0
	v_readlane_b32 s0, v243, 1
	s_addc_u32 s11, s0, s1
	v_ashrrev_i32_e32 v0, 2, v135
	s_movk_i32 s0, 0xffc0
	v_and_or_b32 v134, v0, s0, v181
	s_lshl_b32 s0, s2, 7
	v_lshrrev_b32_e32 v0, 2, v135
	s_and_b32 s0, s0, 0x780
	v_and_b32_e32 v136, 12, v0
	v_lshlrev_b32_e32 v0, 1, v136
	v_add_u32_e32 v138, s0, v134
	v_cmp_gt_u32_e32 vcc, 2, v180
	v_lshlrev_b32_e32 v132, 14, v180
	v_lshl_add_u64 v[130:131], s[10:11], 0, v[0:1]
	v_ashrrev_i32_e32 v139, 31, v138
	s_waitcnt vmcnt(0)
	s_barrier
	s_and_saveexec_b64 s[10:11], vcc
	s_xor_b64 s[10:11], exec, s[10:11]
	s_cbranch_execz .LBB0_897
	v_mov_b32_e32 v133, v1
	v_cvt_pk_bf16_f32 v126, v126, v127
	v_cvt_pk_bf16_f32 v127, v128, v129
	v_lshl_add_u64 v[128:129], v[138:139], 0, v[132:133]
	v_lshlrev_b64 v[128:129], 5, v[128:129]
	v_lshl_add_u64 v[128:129], v[130:131], 0, v[128:129]
	global_store_dwordx2 v[128:129], v[126:127], off
